# write-through (sc1) 16-byte stores in GEMM2, GEMM4, post and final phases so the grid barrier's L2 write-back finds a clean L2
# speedup vs baseline: 1.0029x; 1.0029x over previous
; #define PG8_STAGE(bufoff, gbase, voff) do { _Pragma("unroll") for (int _i = 0; _i < 2; ++_i) \
;         __builtin_amdgcn_global_load_lds((const unsigned*)((const char*)(gbase) + (voff)[_i]), (LAS unsigned*)(lds + (bufoff) + ldsw + _i * 8192), 16, 0, 0); } while (0)
; #define PG8_LDA(dst, b, h) do { _Pragma("unroll") for (int m = 0; m < 4; ++m) _Pragma("unroll") for (int k = 0; k < 2; ++k) dst[m][k] = *(const LAS h16x8*)(lds + PG8_SA(b, h) + aoff + m * 2048 + k * 1024); } while (0)
; #define PG8_LDB(dst, b, h) do { _Pragma("unroll") for (int n = 0; n < 2; ++n) _Pragma("unroll") for (int k = 0; k < 2; ++k) dst[n][k] = *(const LAS h16x8*)(lds + PG8_SB(b, h) + boff + n * 2048 + k * 1024); } while (0)
; #define PG8_MMA(ai, bj, At, Bt) do { __builtin_amdgcn_s_setprio(1); _Pragma("unroll") for (int m = 0; m < 4; ++m) _Pragma("unroll") for (int n = 0; n < 2; ++n) _Pragma("unroll") for (int k = 0; k < 2; ++k) \
;         acc[ai][bj][m][n] = __builtin_amdgcn_mfma_f32_16x16x32_f16(Bt[n][k], At[m][k], acc[ai][bj][m][n], 0, 0, 0); __builtin_amdgcn_s_setprio(0); } while (0)
; #define PG8_WAIT_L(n) asm volatile("s_waitcnt lgkmcnt(" #n ")" ::: "memory")
; #define PG8_BAR __builtin_amdgcn_s_barrier()
; #define PG8_SCHED __builtin_amdgcn_sched_barrier(0)
; template <class Epi>
; __device__ __forceinline__ void gemm_phase(LAS unsigned char* lds, const Gemm g, const StaticOrder& S, const Epi& E) {
;     ...
;             const char* a1 = cA + (size_t)(t + 1) * kstep;
;             const char* a2 = last ? nA : cA + (size_t)(t + 2) * kstep; const char* b2 = last ? nB : cB + (size_t)(t + 2) * kstep;
;             const char* a3 = a2 + kstep; const char* b3 = b2 + kstep;
;             PG8_LDB(B0, 0, 0); PG8_SCHED; PG8_LDA(At, 0, 0); PG8_STAGE(PG8_SA(1, 1), a1 + hstep, voffA);
;             PG8_WAIT_L(8); PG8_BAR; PG8_WAIT_L(0); PG8_MMA(0, 0, At, B0); PG8_BAR; PG8_SCHED;
;             PG8_LDB(B1, 0, 1); PG8_STAGE(PG8_SB(0, 0), b2, voffB);
;             PG8_BAR; PG8_WAIT_L(0); PG8_MMA(0, 1, At, B1); PG8_BAR;
;             PG8_LDA(At, 0, 1); PG8_STAGE(PG8_SA(0, 0), a2, voffA);
;             PG8_BAR; PG8_WAIT_L(0); PG8_MMA(1, 0, At, B0); PG8_BAR; PG8_SCHED;
.LBB0_356:
	ds_read_b128 v[152:155], v149
	ds_read_b128 v[156:159], v149 offset:1024
	ds_read_b128 v[160:163], v149 offset:2048
	ds_read_b128 v[164:167], v149 offset:3072
	s_add_u32 s34, s46, 0xfff80080
	s_addc_u32 s35, s47, -1
	s_cmp_eq_u32 s15, 28
	s_cselect_b32 s53, s27, s35
	s_cselect_b32 s52, s94, s34
	s_cselect_b32 s49, s25, s14
	s_cselect_b32 s48, s95, s96
	v_lshl_add_u64 v[202:203], s[46:47], 0, v[138:139]
	s_add_i32 m0, s23, 0xc000
	ds_read_b128 v[170:173], v150
	ds_read_b128 v[174:177], v150 offset:1024
	ds_read_b128 v[178:181], v150 offset:2048
	ds_read_b128 v[182:185], v150 offset:3072
	ds_read_b128 v[186:189], v150 offset:4096
	ds_read_b128 v[190:193], v150 offset:5120
	ds_read_b128 v[194:197], v150 offset:6144
	ds_read_b128 v[198:201], v150 offset:7168
	global_load_lds_dwordx4 v[202:203], off
	v_lshl_add_u64 v[202:203], s[46:47], 0, v[140:141]
	s_add_i32 m0, s23, 0xe000
	s_nop 0
	global_load_lds_dwordx4 v[202:203], off
	s_waitcnt lgkmcnt(8)
	s_barrier
	s_waitcnt lgkmcnt(0)
	s_waitcnt lgkmcnt(0)
	v_mfma_f32_16x16x32_f16 v[124:127], v[152:155], v[170:173], v[124:127]
	v_mfma_f32_16x16x32_f16 v[120:123], v[160:163], v[170:173], v[120:123]
	v_mfma_f32_16x16x32_f16 v[116:119], v[152:155], v[178:181], v[116:119]
	v_mfma_f32_16x16x32_f16 v[112:115], v[160:163], v[178:181], v[112:115]
	v_mfma_f32_16x16x32_f16 v[100:103], v[152:155], v[186:189], v[100:103]
	v_mfma_f32_16x16x32_f16 v[96:99], v[160:163], v[186:189], v[96:99]
	v_mfma_f32_16x16x32_f16 v[84:87], v[152:155], v[194:197], v[84:87]
	v_mfma_f32_16x16x32_f16 v[80:83], v[160:163], v[194:197], v[80:83]
	v_mfma_f32_16x16x32_f16 v[124:127], v[156:159], v[174:177], v[124:127]
	v_mfma_f32_16x16x32_f16 v[120:123], v[164:167], v[174:177], v[120:123]
	v_mfma_f32_16x16x32_f16 v[116:119], v[156:159], v[182:185], v[116:119]
	v_mfma_f32_16x16x32_f16 v[112:115], v[164:167], v[182:185], v[112:115]
	v_mfma_f32_16x16x32_f16 v[100:103], v[156:159], v[190:193], v[100:103]
	v_mfma_f32_16x16x32_f16 v[96:99], v[164:167], v[190:193], v[96:99]
	v_mfma_f32_16x16x32_f16 v[84:87], v[156:159], v[198:201], v[84:87]
	v_mfma_f32_16x16x32_f16 v[80:83], v[164:167], v[198:201], v[80:83]
	s_barrier
	s_add_i32 s34, s88, s78
	v_lshl_add_u64 v[218:219], s[48:49], 0, v[132:133]
	s_mov_b32 m0, s34
	ds_read_b128 v[202:205], v151
	ds_read_b128 v[206:209], v151 offset:1024
	ds_read_b128 v[210:213], v151 offset:2048
	ds_read_b128 v[214:217], v151 offset:3072
	global_load_lds_dwordx4 v[218:219], off
	v_lshl_add_u64 v[220:221], s[48:49], 0, v[136:137]
	s_add_i32 m0, s34, 0x2000
	s_nop 0
	global_load_lds_dwordx4 v[220:221], off
	s_barrier
	s_waitcnt lgkmcnt(0)
	s_waitcnt lgkmcnt(0)
	v_mfma_f32_16x16x32_f16 v[108:111], v[202:205], v[170:173], v[108:111]
	v_mfma_f32_16x16x32_f16 v[104:107], v[210:213], v[170:173], v[104:107]
	v_mfma_f32_16x16x32_f16 v[92:95], v[202:205], v[178:181], v[92:95]
	v_mfma_f32_16x16x32_f16 v[88:91], v[210:213], v[178:181], v[88:91]
	v_mfma_f32_16x16x32_f16 v[76:79], v[202:205], v[186:189], v[76:79]
	v_mfma_f32_16x16x32_f16 v[72:75], v[210:213], v[186:189], v[72:75]
	v_mfma_f32_16x16x32_f16 v[68:71], v[202:205], v[194:197], v[68:71]
	v_mfma_f32_16x16x32_f16 v[64:67], v[210:213], v[194:197], v[64:67]
	v_mfma_f32_16x16x32_f16 v[108:111], v[206:209], v[174:177], v[108:111]
	v_mfma_f32_16x16x32_f16 v[104:107], v[214:217], v[174:177], v[104:107]
	v_mfma_f32_16x16x32_f16 v[92:95], v[206:209], v[182:185], v[92:95]
	v_mfma_f32_16x16x32_f16 v[88:91], v[214:217], v[182:185], v[88:91]
	v_mfma_f32_16x16x32_f16 v[76:79], v[206:209], v[190:193], v[76:79]
	v_mfma_f32_16x16x32_f16 v[72:75], v[214:217], v[190:193], v[72:75]
	v_mfma_f32_16x16x32_f16 v[68:71], v[206:209], v[198:201], v[68:71]
	v_mfma_f32_16x16x32_f16 v[64:67], v[214:217], v[198:201], v[64:67]
	s_mov_b32 m0, s23
	v_lshl_add_u64 v[222:223], s[52:53], 0, v[128:129]
	s_barrier
	ds_read_b128 v[170:173], v150 offset:16384
	ds_read_b128 v[174:177], v150 offset:17408
	ds_read_b128 v[178:181], v150 offset:18432
	ds_read_b128 v[182:185], v150 offset:19456
	ds_read_b128 v[186:189], v150 offset:20480
	ds_read_b128 v[190:193], v150 offset:21504
	ds_read_b128 v[194:197], v150 offset:22528
	ds_read_b128 v[198:201], v150 offset:23552
	global_load_lds_dwordx4 v[222:223], off
	v_lshl_add_u64 v[224:225], s[52:53], 0, v[134:135]
	s_mov_b32 m0, s80
	s_nop 0
	global_load_lds_dwordx4 v[224:225], off
	s_barrier
	s_waitcnt lgkmcnt(0)
	s_waitcnt lgkmcnt(0)
	v_mfma_f32_16x16x32_f16 v[60:63], v[152:155], v[170:173], v[60:63]
	v_mfma_f32_16x16x32_f16 v[56:59], v[160:163], v[170:173], v[56:59]
	v_mfma_f32_16x16x32_f16 v[52:55], v[152:155], v[178:181], v[52:55]
	v_mfma_f32_16x16x32_f16 v[48:51], v[160:163], v[178:181], v[48:51]
	v_mfma_f32_16x16x32_f16 v[36:39], v[152:155], v[186:189], v[36:39]
	v_mfma_f32_16x16x32_f16 v[32:35], v[160:163], v[186:189], v[32:35]
	v_mfma_f32_16x16x32_f16 v[20:23], v[152:155], v[194:197], v[20:23]
	v_mfma_f32_16x16x32_f16 v[16:19], v[160:163], v[194:197], v[16:19]
	v_mfma_f32_16x16x32_f16 v[60:63], v[156:159], v[174:177], v[60:63]
	v_mfma_f32_16x16x32_f16 v[56:59], v[164:167], v[174:177], v[56:59]
	v_mfma_f32_16x16x32_f16 v[52:55], v[156:159], v[182:185], v[52:55]
	v_mfma_f32_16x16x32_f16 v[48:51], v[164:167], v[182:185], v[48:51]
	v_mfma_f32_16x16x32_f16 v[36:39], v[156:159], v[190:193], v[36:39]
	v_mfma_f32_16x16x32_f16 v[32:35], v[164:167], v[190:193], v[32:35]
	v_mfma_f32_16x16x32_f16 v[20:23], v[156:159], v[198:201], v[20:23]
	v_mfma_f32_16x16x32_f16 v[16:19], v[164:167], v[198:201], v[16:19]
	s_barrier
; #define PG8_STAGE(bufoff, gbase, voff) do { _Pragma("unroll") for (int _i = 0; _i < 2; ++_i) \
;         __builtin_amdgcn_global_load_lds((const unsigned*)((const char*)(gbase) + (voff)[_i]), (LAS unsigned*)(lds + (bufoff) + ldsw + _i * 8192), 16, 0, 0); } while (0)
; #define PG8_LDA(dst, b, h) do { _Pragma("unroll") for (int m = 0; m < 4; ++m) _Pragma("unroll") for (int k = 0; k < 2; ++k) dst[m][k] = *(const LAS h16x8*)(lds + PG8_SA(b, h) + aoff + m * 2048 + k * 1024); } while (0)
; #define PG8_LDB(dst, b, h) do { _Pragma("unroll") for (int n = 0; n < 2; ++n) _Pragma("unroll") for (int k = 0; k < 2; ++k) dst[n][k] = *(const LAS h16x8*)(lds + PG8_SB(b, h) + boff + n * 2048 + k * 1024); } while (0)
; #define PG8_MMA(ai, bj, At, Bt) do { __builtin_amdgcn_s_setprio(1); _Pragma("unroll") for (int m = 0; m < 4; ++m) _Pragma("unroll") for (int n = 0; n < 2; ++n) _Pragma("unroll") for (int k = 0; k < 2; ++k) \
;         acc[ai][bj][m][n] = __builtin_amdgcn_mfma_f32_16x16x32_f16(Bt[n][k], At[m][k], acc[ai][bj][m][n], 0, 0, 0); __builtin_amdgcn_s_setprio(0); } while (0)
; #define PG8_WAIT_V(n) asm volatile("s_waitcnt vmcnt(" #n ")" ::: "memory")
; #define PG8_WAIT_L(n) asm volatile("s_waitcnt lgkmcnt(" #n ")" ::: "memory")
; #define PG8_BAR __builtin_amdgcn_s_barrier()
; #define PG8_SCHED __builtin_amdgcn_sched_barrier(0)
; template <class Epi>
; __device__ __forceinline__ void gemm_phase(LAS unsigned char* lds, const Gemm g, const StaticOrder& S, const Epi& E) {
;     ...
;             PG8_STAGE(PG8_SB(0, 1), b2 + hstep, voffB);
;             PG8_WAIT_V(6); PG8_BAR; PG8_MMA(1, 1, At, B1); PG8_BAR;
;             PG8_LDB(B0, 1, 0); PG8_SCHED; PG8_LDA(At, 1, 0); PG8_STAGE(PG8_SA(0, 1), a2 + hstep, voffA);
;             PG8_WAIT_L(8); PG8_BAR; PG8_WAIT_L(0); PG8_MMA(0, 0, At, B0); PG8_BAR; PG8_SCHED;
;             PG8_LDB(B1, 1, 1); PG8_STAGE(PG8_SB(1, 0), b3, voffB);
;             PG8_BAR; PG8_WAIT_L(0); PG8_MMA(0, 1, At, B1); PG8_BAR;
	s_add_u32 s34, s48, 0x80000
	s_addc_u32 s35, s49, 0
	s_add_i32 s97, s89, s78
	v_lshl_add_u64 v[152:153], s[34:35], 0, v[132:133]
	s_mov_b32 m0, s97
	s_nop 0
	global_load_lds_dwordx4 v[152:153], off
	v_lshl_add_u64 v[152:153], s[34:35], 0, v[136:137]
	s_add_i32 m0, s97, 0x2000
	s_nop 0
	global_load_lds_dwordx4 v[152:153], off
	s_waitcnt vmcnt(6)
	s_barrier
	v_mfma_f32_16x16x32_f16 v[44:47], v[202:205], v[170:173], v[44:47]
	v_mfma_f32_16x16x32_f16 v[40:43], v[210:213], v[170:173], v[40:43]
	v_mfma_f32_16x16x32_f16 v[28:31], v[202:205], v[178:181], v[28:31]
	v_mfma_f32_16x16x32_f16 v[24:27], v[210:213], v[178:181], v[24:27]
	v_mfma_f32_16x16x32_f16 v[12:15], v[202:205], v[186:189], v[12:15]
	v_mfma_f32_16x16x32_f16 v[8:11], v[210:213], v[186:189], v[8:11]
	v_mfma_f32_16x16x32_f16 v[4:7], v[202:205], v[194:197], v[4:7]
	v_mfma_f32_16x16x32_f16 v[0:3], v[210:213], v[194:197], v[0:3]
	v_mfma_f32_16x16x32_f16 v[44:47], v[206:209], v[174:177], v[44:47]
	v_mfma_f32_16x16x32_f16 v[40:43], v[214:217], v[174:177], v[40:43]
	v_mfma_f32_16x16x32_f16 v[28:31], v[206:209], v[182:185], v[28:31]
	v_mfma_f32_16x16x32_f16 v[24:27], v[214:217], v[182:185], v[24:27]
	v_mfma_f32_16x16x32_f16 v[12:15], v[206:209], v[190:193], v[12:15]
	v_mfma_f32_16x16x32_f16 v[8:11], v[214:217], v[190:193], v[8:11]
	v_mfma_f32_16x16x32_f16 v[4:7], v[206:209], v[198:201], v[4:7]
	v_mfma_f32_16x16x32_f16 v[0:3], v[214:217], v[198:201], v[0:3]
	s_add_i32 s97, 0, 0x18000
	v_add_u32_e32 v164, s97, v147
	s_barrier
	ds_read_b128 v[152:155], v164
	ds_read_b128 v[156:159], v164 offset:1024
	ds_read_b128 v[160:163], v164 offset:2048
	ds_read_b128 v[164:167], v164 offset:3072
	s_add_u32 s34, s52, 0x80000
	s_addc_u32 s35, s53, 0
	s_mov_b32 m0, s81
	v_lshl_add_u64 v[202:203], s[34:35], 0, v[128:129]
	ds_read_b128 v[170:173], v150 offset:32768
	ds_read_b128 v[174:177], v150 offset:33792
	ds_read_b128 v[178:181], v150 offset:34816
	ds_read_b128 v[182:185], v150 offset:35840
	ds_read_b128 v[186:189], v150 offset:36864
	ds_read_b128 v[190:193], v150 offset:37888
	ds_read_b128 v[194:197], v150 offset:38912
	ds_read_b128 v[198:201], v150 offset:39936
	global_load_lds_dwordx4 v[202:203], off
	v_lshl_add_u64 v[202:203], s[34:35], 0, v[134:135]
	s_mov_b32 m0, s82
	s_nop 0
	global_load_lds_dwordx4 v[202:203], off
	s_waitcnt lgkmcnt(8)
	s_barrier
	s_waitcnt lgkmcnt(0)
	s_waitcnt lgkmcnt(0)
	v_mfma_f32_16x16x32_f16 v[124:127], v[152:155], v[170:173], v[124:127]
	v_mfma_f32_16x16x32_f16 v[120:123], v[160:163], v[170:173], v[120:123]
	v_mfma_f32_16x16x32_f16 v[116:119], v[152:155], v[178:181], v[116:119]
	v_mfma_f32_16x16x32_f16 v[112:115], v[160:163], v[178:181], v[112:115]
	v_mfma_f32_16x16x32_f16 v[100:103], v[152:155], v[186:189], v[100:103]
	v_mfma_f32_16x16x32_f16 v[96:99], v[160:163], v[186:189], v[96:99]
	v_mfma_f32_16x16x32_f16 v[84:87], v[152:155], v[194:197], v[84:87]
	v_mfma_f32_16x16x32_f16 v[80:83], v[160:163], v[194:197], v[80:83]
	v_mfma_f32_16x16x32_f16 v[124:127], v[156:159], v[174:177], v[124:127]
	v_mfma_f32_16x16x32_f16 v[120:123], v[164:167], v[174:177], v[120:123]
	v_mfma_f32_16x16x32_f16 v[116:119], v[156:159], v[182:185], v[116:119]
	v_mfma_f32_16x16x32_f16 v[112:115], v[164:167], v[182:185], v[112:115]
	v_mfma_f32_16x16x32_f16 v[100:103], v[156:159], v[190:193], v[100:103]
	v_mfma_f32_16x16x32_f16 v[96:99], v[164:167], v[190:193], v[96:99]
	v_mfma_f32_16x16x32_f16 v[84:87], v[156:159], v[198:201], v[84:87]
	v_mfma_f32_16x16x32_f16 v[80:83], v[164:167], v[198:201], v[80:83]
	s_barrier
	s_add_i32 s52, 0, 0x1c000
	s_add_i32 s34, s97, s78
	v_add_u32_e32 v169, s52, v147
	v_lshl_add_u64 v[218:219], v[218:219], 0, s[8:9]
	s_mov_b32 m0, s34
	ds_read_b128 v[202:205], v169
	ds_read_b128 v[206:209], v169 offset:1024
	ds_read_b128 v[210:213], v169 offset:2048
	ds_read_b128 v[214:217], v169 offset:3072
	global_load_lds_dwordx4 v[218:219], off
	v_lshl_add_u64 v[218:219], v[220:221], 0, s[8:9]
	s_add_i32 m0, s34, 0x2000
	s_nop 0
	global_load_lds_dwordx4 v[218:219], off
	s_barrier
	s_waitcnt lgkmcnt(0)
	s_waitcnt lgkmcnt(0)
	v_mfma_f32_16x16x32_f16 v[108:111], v[202:205], v[170:173], v[108:111]
	v_mfma_f32_16x16x32_f16 v[104:107], v[210:213], v[170:173], v[104:107]
	v_mfma_f32_16x16x32_f16 v[92:95], v[202:205], v[178:181], v[92:95]
	v_mfma_f32_16x16x32_f16 v[88:91], v[210:213], v[178:181], v[88:91]
	v_mfma_f32_16x16x32_f16 v[76:79], v[202:205], v[186:189], v[76:79]
	v_mfma_f32_16x16x32_f16 v[72:75], v[210:213], v[186:189], v[72:75]
	v_mfma_f32_16x16x32_f16 v[68:71], v[202:205], v[194:197], v[68:71]
	v_mfma_f32_16x16x32_f16 v[64:67], v[210:213], v[194:197], v[64:67]
	v_mfma_f32_16x16x32_f16 v[108:111], v[206:209], v[174:177], v[108:111]
	v_mfma_f32_16x16x32_f16 v[104:107], v[214:217], v[174:177], v[104:107]
	v_mfma_f32_16x16x32_f16 v[92:95], v[206:209], v[182:185], v[92:95]
	v_mfma_f32_16x16x32_f16 v[88:91], v[214:217], v[182:185], v[88:91]
	v_mfma_f32_16x16x32_f16 v[76:79], v[206:209], v[190:193], v[76:79]
	v_mfma_f32_16x16x32_f16 v[72:75], v[214:217], v[190:193], v[72:75]
	v_mfma_f32_16x16x32_f16 v[68:71], v[206:209], v[198:201], v[68:71]
	v_mfma_f32_16x16x32_f16 v[64:67], v[214:217], v[198:201], v[64:67]
	s_mov_b32 m0, s85
	v_lshl_add_u64 v[218:219], v[222:223], 0, s[8:9]
	s_barrier
	ds_read_b128 v[170:173], v150 offset:49152
	ds_read_b128 v[174:177], v150 offset:50176
	ds_read_b128 v[178:181], v150 offset:51200
	ds_read_b128 v[182:185], v150 offset:52224
	ds_read_b128 v[186:189], v150 offset:53248
	ds_read_b128 v[190:193], v150 offset:54272
	ds_read_b128 v[194:197], v150 offset:55296
	ds_read_b128 v[198:201], v150 offset:56320
	global_load_lds_dwordx4 v[218:219], off
	v_lshl_add_u64 v[218:219], v[224:225], 0, s[8:9]
	s_mov_b32 m0, s86
	s_nop 0
	global_load_lds_dwordx4 v[218:219], off
	s_barrier
; #define PG8_STAGE(bufoff, gbase, voff) do { _Pragma("unroll") for (int _i = 0; _i < 2; ++_i) \
;         __builtin_amdgcn_global_load_lds((const unsigned*)((const char*)(gbase) + (voff)[_i]), (LAS unsigned*)(lds + (bufoff) + ldsw + _i * 8192), 16, 0, 0); } while (0)
; #define PG8_MMA(ai, bj, At, Bt) do { __builtin_amdgcn_s_setprio(1); _Pragma("unroll") for (int m = 0; m < 4; ++m) _Pragma("unroll") for (int n = 0; n < 2; ++n) _Pragma("unroll") for (int k = 0; k < 2; ++k) \
;         acc[ai][bj][m][n] = __builtin_amdgcn_mfma_f32_16x16x32_f16(Bt[n][k], At[m][k], acc[ai][bj][m][n], 0, 0, 0); __builtin_amdgcn_s_setprio(0); } while (0)
; #define PG8_WAIT_V(n) asm volatile("s_waitcnt vmcnt(" #n ")" ::: "memory")
; #define PG8_WAIT_L(n) asm volatile("s_waitcnt lgkmcnt(" #n ")" ::: "memory")
; #define PG8_BAR __builtin_amdgcn_s_barrier()
; #define PG8_SCHED __builtin_amdgcn_sched_barrier(0)
; template <class Epi>
; __device__ __forceinline__ void gemm_phase(LAS unsigned char* lds, const Gemm g, const StaticOrder& S, const Epi& E) {
;     ...
;             PG8_BAR; PG8_WAIT_L(0); PG8_MMA(1, 0, At, B0); PG8_BAR; PG8_SCHED;
;             PG8_STAGE(PG8_SB(1, 1), b3 + hstep, voffB);
;             PG8_WAIT_V(6); PG8_BAR; PG8_MMA(1, 1, At, B1); PG8_BAR;
	s_waitcnt lgkmcnt(0)
	s_waitcnt lgkmcnt(0)
	v_mfma_f32_16x16x32_f16 v[60:63], v[152:155], v[170:173], v[60:63]
	v_mfma_f32_16x16x32_f16 v[56:59], v[160:163], v[170:173], v[56:59]
	v_mfma_f32_16x16x32_f16 v[52:55], v[152:155], v[178:181], v[52:55]
	v_mfma_f32_16x16x32_f16 v[48:51], v[160:163], v[178:181], v[48:51]
	v_mfma_f32_16x16x32_f16 v[36:39], v[152:155], v[186:189], v[36:39]
	v_mfma_f32_16x16x32_f16 v[32:35], v[160:163], v[186:189], v[32:35]
	v_mfma_f32_16x16x32_f16 v[20:23], v[152:155], v[194:197], v[20:23]
	v_mfma_f32_16x16x32_f16 v[16:19], v[160:163], v[194:197], v[16:19]
	v_mfma_f32_16x16x32_f16 v[60:63], v[156:159], v[174:177], v[60:63]
	v_mfma_f32_16x16x32_f16 v[56:59], v[164:167], v[174:177], v[56:59]
	v_mfma_f32_16x16x32_f16 v[52:55], v[156:159], v[182:185], v[52:55]
	v_mfma_f32_16x16x32_f16 v[48:51], v[164:167], v[182:185], v[48:51]
	v_mfma_f32_16x16x32_f16 v[36:39], v[156:159], v[190:193], v[36:39]
	v_mfma_f32_16x16x32_f16 v[32:35], v[164:167], v[190:193], v[32:35]
	v_mfma_f32_16x16x32_f16 v[20:23], v[156:159], v[198:201], v[20:23]
	v_mfma_f32_16x16x32_f16 v[16:19], v[164:167], v[198:201], v[16:19]
	s_barrier
	s_add_u32 s34, s48, 0x80080
	s_addc_u32 s35, s49, 0
	s_add_i32 s48, s52, s78
	v_lshl_add_u64 v[152:153], s[34:35], 0, v[132:133]
	s_mov_b32 m0, s48
	s_nop 0
	global_load_lds_dwordx4 v[152:153], off
	v_lshl_add_u64 v[152:153], s[34:35], 0, v[136:137]
	s_add_i32 m0, s48, 0x2000
	s_nop 0
	global_load_lds_dwordx4 v[152:153], off
	s_waitcnt vmcnt(6)
	s_barrier
	v_mfma_f32_16x16x32_f16 v[44:47], v[202:205], v[170:173], v[44:47]
	v_mfma_f32_16x16x32_f16 v[40:43], v[210:213], v[170:173], v[40:43]
	v_mfma_f32_16x16x32_f16 v[28:31], v[202:205], v[178:181], v[28:31]
	v_mfma_f32_16x16x32_f16 v[24:27], v[210:213], v[178:181], v[24:27]
	v_mfma_f32_16x16x32_f16 v[12:15], v[202:205], v[186:189], v[12:15]
	v_mfma_f32_16x16x32_f16 v[8:11], v[210:213], v[186:189], v[8:11]
	v_mfma_f32_16x16x32_f16 v[4:7], v[202:205], v[194:197], v[4:7]
	v_mfma_f32_16x16x32_f16 v[0:3], v[210:213], v[194:197], v[0:3]
	v_mfma_f32_16x16x32_f16 v[44:47], v[206:209], v[174:177], v[44:47]
	v_mfma_f32_16x16x32_f16 v[40:43], v[214:217], v[174:177], v[40:43]
	v_mfma_f32_16x16x32_f16 v[28:31], v[206:209], v[182:185], v[28:31]
	v_mfma_f32_16x16x32_f16 v[24:27], v[214:217], v[182:185], v[24:27]
	v_mfma_f32_16x16x32_f16 v[12:15], v[206:209], v[190:193], v[12:15]
	v_mfma_f32_16x16x32_f16 v[8:11], v[214:217], v[190:193], v[8:11]
	v_mfma_f32_16x16x32_f16 v[4:7], v[206:209], v[198:201], v[4:7]
	v_mfma_f32_16x16x32_f16 v[0:3], v[214:217], v[198:201], v[0:3]
	s_add_i32 s15, s15, 2
	s_add_u32 s46, s46, 0x100
	s_addc_u32 s47, s47, 0
	s_add_u32 s96, s96, 0x100
	s_addc_u32 s14, s14, 0
	s_cmp_gt_u32 s15, 29
	s_barrier
	s_cbranch_scc0 .LBB0_356
;     __device__ __forceinline__ void operator()(const f32x4 (&acc)[2][2][4][2], const pg8::Unit& u, int wr, int wc, int fr, int fq) const {
;         const int row0 = u.pm * 256 + wr * 64 + fr, col0 = u.pn * 256 + wc * 32 + 8 * fq;
; #pragma unroll
;         for (int ai = 0; ai < 2; ++ai)
; #pragma unroll
;             for (int m = 0; m < 4; ++m) { const size_t r = (size_t)(row0 + ai * 128 + m * 16);
; #pragma unroll
;                 for (int bj = 0; bj < 2; ++bj) { const f32x4 v0 = acc[ai][bj][m][0], v1 = acc[ai][bj][m][1]; h16x8 o;
; #pragma unroll
;                     for (int e = 0; e < 4; ++e) { o[e] = (h16)v0[e]; o[4 + e] = (h16)v1[e]; }
;                     *(h16x8*)(O1 + r * 1024 + col0 + bj * 128) = o; } }
	v_lshl_add_u32 v152, s22, 8, v146
	v_lshl_or_b32 v154, s93, 8, v148
	v_ashrrev_i32_e32 v153, 31, v152
	v_ashrrev_i32_e32 v155, 31, v154
	v_lshlrev_b64 v[156:157], 11, v[152:153]
	v_cvt_pk_f16_f32 v123, v122, v123
	v_cvt_pk_f16_f32 v122, v120, v121
	v_cvt_pk_f16_f32 v121, v126, v127
	v_cvt_pk_f16_f32 v120, v124, v125
	v_lshl_add_u64 v[124:125], s[6:7], 0, v[156:157]
	v_lshlrev_b64 v[126:127], 1, v[154:155]
	v_lshl_add_u64 v[124:125], v[124:125], 0, v[126:127]
	v_cvt_pk_f16_f32 v107, v106, v107
	v_cvt_pk_f16_f32 v106, v104, v105
	v_cvt_pk_f16_f32 v105, v110, v111
	v_cvt_pk_f16_f32 v104, v108, v109
	global_store_dwordx4 v[124:125], v[104:107], off offset:256 sc1
	v_cvt_pk_f16_f32 v91, v90, v91
	v_cvt_pk_f16_f32 v90, v88, v89
	v_or_b32_e32 v104, 16, v152
	v_ashrrev_i32_e32 v105, 31, v104
	v_lshlrev_b64 v[108:109], 11, v[104:105]
	v_lshl_add_u64 v[108:109], s[6:7], 0, v[108:109]
	v_lshl_add_u64 v[108:109], v[108:109], 0, v[126:127]
	v_cvt_pk_f16_f32 v89, v94, v95
	v_cvt_pk_f16_f32 v88, v92, v93
	global_store_dwordx4 v[108:109], v[88:91], off offset:256 sc1
	v_cvt_pk_f16_f32 v59, v58, v59
	v_cvt_pk_f16_f32 v58, v56, v57
	v_or_b32_e32 v88, 32, v152
	v_ashrrev_i32_e32 v89, 31, v88
	v_cvt_pk_f16_f32 v57, v62, v63
	v_add_co_u32_e32 v62, vcc, s90, v124
	v_lshlrev_b64 v[92:93], 11, v[88:89]
	s_nop 0
	v_addc_co_u32_e32 v63, vcc, 0, v125, vcc
	v_lshl_add_u64 v[92:93], s[6:7], 0, v[92:93]
	v_cvt_pk_f16_f32 v43, v42, v43
	v_cvt_pk_f16_f32 v42, v40, v41
	v_cvt_pk_f16_f32 v41, v46, v47
	v_add_co_u32_e32 v46, vcc, s91, v124
	v_lshl_add_u64 v[92:93], v[92:93], 0, v[126:127]
	v_cvt_pk_f16_f32 v75, v74, v75
	v_cvt_pk_f16_f32 v74, v72, v73
	v_cvt_pk_f16_f32 v73, v78, v79
	v_cvt_pk_f16_f32 v72, v76, v77
	v_addc_co_u32_e32 v47, vcc, 0, v125, vcc
	global_store_dwordx4 v[92:93], v[72:75], off offset:256 sc1
	v_cvt_pk_f16_f32 v27, v26, v27
	v_cvt_pk_f16_f32 v26, v24, v25
	v_or_b32_e32 v72, 48, v152
	v_cvt_pk_f16_f32 v25, v30, v31
	v_add_co_u32_e32 v30, vcc, s92, v124
	v_ashrrev_i32_e32 v73, 31, v72
	s_nop 0
	v_addc_co_u32_e32 v31, vcc, 0, v125, vcc
	v_lshlrev_b64 v[76:77], 11, v[72:73]
	v_cvt_pk_f16_f32 v11, v10, v11
	v_cvt_pk_f16_f32 v10, v8, v9
	v_cvt_pk_f16_f32 v9, v14, v15
	v_add_co_u32_e32 v14, vcc, 0x58000, v124
	v_lshl_add_u64 v[76:77], s[6:7], 0, v[76:77]
	v_cvt_pk_f16_f32 v56, v60, v61
	v_lshl_add_u64 v[60:61], v[124:125], 0, s[10:11]
	v_cvt_pk_f16_f32 v40, v44, v45
	v_lshl_add_u64 v[44:45], v[124:125], 0, s[12:13]
	v_cvt_pk_f16_f32 v24, v28, v29
	v_lshl_add_u64 v[28:29], v[124:125], 0, s[18:19]
	v_cvt_pk_f16_f32 v8, v12, v13
	v_addc_co_u32_e32 v15, vcc, 0, v125, vcc
	v_cvt_pk_f16_f32 v107, v114, v115
	v_cvt_pk_f16_f32 v106, v112, v113
	v_cvt_pk_f16_f32 v105, v118, v119
	v_cvt_pk_f16_f32 v104, v116, v117
	v_cvt_pk_f16_f32 v91, v98, v99
	v_cvt_pk_f16_f32 v90, v96, v97
	v_cvt_pk_f16_f32 v89, v102, v103
	v_cvt_pk_f16_f32 v88, v100, v101
	v_cvt_pk_f16_f32 v75, v82, v83
	v_cvt_pk_f16_f32 v74, v80, v81
	v_cvt_pk_f16_f32 v73, v86, v87
	v_cvt_pk_f16_f32 v72, v84, v85
	v_lshl_add_u64 v[76:77], v[76:77], 0, v[126:127]
	v_cvt_pk_f16_f32 v67, v66, v67
	v_cvt_pk_f16_f32 v66, v64, v65
	v_cvt_pk_f16_f32 v65, v70, v71
	v_cvt_pk_f16_f32 v64, v68, v69
	global_store_dwordx4 v[60:61], v[40:43], off offset:256 sc1
	global_store_dwordx4 v[44:45], v[24:27], off offset:256 sc1
	global_store_dwordx4 v[28:29], v[8:11], off offset:256 sc1
	v_cvt_pk_f16_f32 v43, v50, v51
	v_cvt_pk_f16_f32 v42, v48, v49
	v_cvt_pk_f16_f32 v41, v54, v55
	v_cvt_pk_f16_f32 v40, v52, v53
	v_cvt_pk_f16_f32 v27, v34, v35
	v_cvt_pk_f16_f32 v26, v32, v33
	v_cvt_pk_f16_f32 v25, v38, v39
	v_cvt_pk_f16_f32 v24, v36, v37
	v_cvt_pk_f16_f32 v11, v18, v19
	v_cvt_pk_f16_f32 v10, v16, v17
	v_cvt_pk_f16_f32 v9, v22, v23
	v_cvt_pk_f16_f32 v8, v20, v21
	v_lshl_add_u64 v[12:13], v[124:125], 0, s[20:21]
	v_cvt_pk_f16_f32 v3, v2, v3
	v_cvt_pk_f16_f32 v2, v0, v1
	v_cvt_pk_f16_f32 v1, v6, v7
	v_cvt_pk_f16_f32 v0, v4, v5
	s_and_b64 vcc, exec, s[0:1]
	s_mov_b32 s93, s24
	s_mov_b32 s22, s26
	s_mov_b64 s[48:49], s[30:31]
	s_mov_b64 s[46:47], s[28:29]
	global_store_dwordx4 v[124:125], v[120:123], off sc1
	global_store_dwordx4 v[108:109], v[104:107], off sc1
	global_store_dwordx4 v[92:93], v[88:91], off sc1
	global_store_dwordx4 v[76:77], v[72:75], off sc1
	global_store_dwordx4 v[76:77], v[64:67], off offset:256 sc1
	global_store_dwordx4 v[62:63], v[56:59], off sc1
	global_store_dwordx4 v[46:47], v[40:43], off sc1
	global_store_dwordx4 v[30:31], v[24:27], off sc1
	global_store_dwordx4 v[14:15], v[8:11], off sc1
	global_store_dwordx4 v[12:13], v[0:3], off offset:256 sc1
	s_cbranch_vccz .LBB0_349
	s_waitcnt vmcnt(0)
	s_cmpk_gt_u32 s33, 0xff
	s_cbranch_scc1 .LBB0_360
	s_barrier

; __device__ __forceinline__ float silu_f(float x) { return x * __builtin_amdgcn_rcpf(1.f + __expf(-x)); }
; __device__ __forceinline__ void phase_post(const Params& p) {
;     ...
;         const f32x4 lg0 = *(const f32x4*)(lg + c), lg1 = *(const f32x4*)(lg + c + 4), lb0 = *(const f32x4*)(lb + c), lb1 = *(const f32x4*)(lb + c + 4);
;         const f32x4 ma0 = *(const f32x4*)(mu0 + c), ma1 = *(const f32x4*)(mu0 + c + 4), mb0 = *(const f32x4*)(mu1 + c), mb1 = *(const f32x4*)(mu1 + c + 4);
; #pragma unroll
;         for (int u = 0; u < 4; ++u) {
;             float y[8], s = 0.f;
; #pragma unroll
;             for (int e = 0; e < 8; ++e) { y[e] = (float)y0[u][e] + (float)y1[u][e]; s += y[e]; }
;             const float mean = red8(s) * (1.f / 64.f); float q = 0.f;
;     ...
;                 o[e] = (h16)(val * silu_f((float)zc[u][e])); }
.LBB0_683:
	s_or_b64 exec, exec, s[30:31]
	v_lshlrev_b32_e32 v36, 2, v8
	global_load_dwordx4 v[44:47], v36, s[20:21]
	global_load_dwordx4 v[40:43], v36, s[22:23]
	global_load_dwordx4 v[12:15], v36, s[20:21] offset:16
	global_load_dwordx4 v[8:11], v36, s[22:23] offset:16
	s_waitcnt vmcnt(19)
	v_cvt_f32_f16_sdwa v141, v96 dst_sel:DWORD dst_unused:UNUSED_PAD src0_sel:WORD_1
	v_cvt_f32_f16_sdwa v151, v84 dst_sel:DWORD dst_unused:UNUSED_PAD src0_sel:WORD_1
	v_cvt_f32_f16_e32 v150, v84
	v_cvt_f32_f16_sdwa v135, v100 dst_sel:DWORD dst_unused:UNUSED_PAD src0_sel:WORD_1
	v_cvt_f32_f16_e32 v134, v100
	v_cvt_f32_f16_sdwa v137, v92 dst_sel:DWORD dst_unused:UNUSED_PAD src0_sel:WORD_1
	v_cvt_f32_f16_e32 v136, v92
	v_cvt_f32_f16_sdwa v139, v88 dst_sel:DWORD dst_unused:UNUSED_PAD src0_sel:WORD_1
	v_cvt_f32_f16_e32 v138, v88
	v_cvt_f32_f16_e32 v140, v96
	v_cvt_f32_f16_sdwa v149, v85 dst_sel:DWORD dst_unused:UNUSED_PAD src0_sel:WORD_1
	v_cvt_f32_f16_e32 v148, v85
	v_cvt_f32_f16_sdwa v85, v101 dst_sel:DWORD dst_unused:UNUSED_PAD src0_sel:WORD_1
	v_cvt_f32_f16_e32 v84, v101
	v_cvt_f32_f16_sdwa v101, v93 dst_sel:DWORD dst_unused:UNUSED_PAD src0_sel:WORD_1
	v_cvt_f32_f16_e32 v100, v93
	v_cvt_f32_f16_sdwa v93, v89 dst_sel:DWORD dst_unused:UNUSED_PAD src0_sel:WORD_1
	v_cvt_f32_f16_e32 v92, v89
	v_cvt_f32_f16_sdwa v89, v97 dst_sel:DWORD dst_unused:UNUSED_PAD src0_sel:WORD_1
	v_cvt_f32_f16_e32 v88, v97
	v_cvt_f32_f16_e32 v154, v98
	v_cvt_f32_f16_sdwa v153, v86 dst_sel:DWORD dst_unused:UNUSED_PAD src0_sel:WORD_1
	v_cvt_f32_f16_e32 v152, v86
	v_mul_f32_e32 v86, 0xbfb8aa3b, v141
	v_cvt_f32_f16_sdwa v147, v90 dst_sel:DWORD dst_unused:UNUSED_PAD src0_sel:WORD_1
	v_cvt_f32_f16_e32 v146, v90
	v_cvt_f32_f16_sdwa v157, v82 dst_sel:DWORD dst_unused:UNUSED_PAD src0_sel:WORD_1
	v_cvt_f32_f16_e32 v156, v82
	v_mul_f32_e32 v82, 0xbfb8aa3b, v140
	v_pk_add_f32 v[160:161], v[100:101], v[92:93]
	v_mul_f32_e32 v90, 0xbfb8aa3b, v88
	v_mul_f32_e32 v92, 0xbfb8aa3b, v89
	v_exp_f32_e32 v86, v86
	v_cvt_f32_f16_sdwa v97, v81 dst_sel:DWORD dst_unused:UNUSED_PAD src0_sel:WORD_1
	v_cvt_f32_f16_e32 v96, v81
	v_cvt_f32_f16_sdwa v155, v98 dst_sel:DWORD dst_unused:UNUSED_PAD src0_sel:WORD_1
	v_pk_add_f32 v[158:159], v[136:137], v[138:139]
	v_exp_f32_e32 v82, v82
	v_exp_f32_e32 v90, v90
	v_exp_f32_e32 v92, v92
	v_cvt_f32_f16_sdwa v145, v94 dst_sel:DWORD dst_unused:UNUSED_PAD src0_sel:WORD_1
	v_cvt_f32_f16_e32 v144, v94
	v_mul_f32_e32 v93, 0xbfb8aa3b, v154
	v_add_f32_e32 v94, 0, v158
	v_exp_f32_e32 v98, v93
	v_add_f32_e32 v93, v159, v94
	v_add_f32_e32 v93, v160, v93
	v_add_f32_e32 v86, 1.0, v86
	v_pk_add_f32 v[100:101], v[96:97], v[148:149] neg_lo:[0,1] neg_hi:[0,1]
	v_add_f32_e32 v94, v161, v93
	v_add_f32_e32 v82, 1.0, v82
	v_add_f32_e32 v90, 1.0, v90
	v_add_f32_e32 v96, 1.0, v92
	v_rcp_f32_e32 v93, v86
	v_mul_f32_e32 v86, 0xbfb8aa3b, v155
	v_rcp_f32_e32 v92, v82
	v_rcp_f32_e32 v138, v90
	v_rcp_f32_e32 v139, v96
	v_exp_f32_e32 v86, v86
	v_pk_mul_f32 v[96:97], v[92:93], v[140:141]
	global_load_dwordx4 v[24:27], v36, s[42:43] offset:16
	global_load_dwordx4 v[28:31], v36, s[44:45] offset:16
	global_load_dwordx4 v[32:35], v36, s[42:43]
	s_nop 0
	global_load_dwordx4 v[36:39], v36, s[44:45]
	v_pk_mul_f32 v[92:93], v[138:139], v[88:89]
	v_add_f32_e32 v88, 1.0, v98
	v_add_f32_e32 v86, 1.0, v86
	v_rcp_f32_e32 v88, v88
	v_rcp_f32_e32 v89, v86
	v_pk_add_f32 v[164:165], v[144:145], v[146:147]
	s_waitcnt vmcnt(22)
	v_cvt_f32_f16_e32 v174, v64
	v_add_f32_e32 v82, v164, v94
	v_pk_mul_f32 v[146:147], v[88:89], v[154:155]
	v_cvt_f32_f16_sdwa v155, v95 dst_sel:DWORD dst_unused:UNUSED_PAD src0_sel:WORD_1
	v_cvt_f32_f16_e32 v154, v95
	v_cvt_f32_f16_sdwa v95, v91 dst_sel:DWORD dst_unused:UNUSED_PAD src0_sel:WORD_1
	v_cvt_f32_f16_e32 v94, v91
	v_add_f32_e32 v82, v165, v82
	v_cvt_f32_f16_sdwa v175, v64 dst_sel:DWORD dst_unused:UNUSED_PAD src0_sel:WORD_1
	v_cvt_f32_f16_sdwa v143, v80 dst_sel:DWORD dst_unused:UNUSED_PAD src0_sel:WORD_1
	v_pk_add_f32 v[94:95], v[154:155], v[94:95]
	v_cvt_f32_f16_e32 v142, v80
	v_add_f32_e32 v82, v94, v82
	v_add_f32_e32 v82, v95, v82
	v_cvt_f32_f16_e32 v98, v99
	v_cvt_f32_f16_sdwa v99, v99 dst_sel:DWORD dst_unused:UNUSED_PAD src0_sel:WORD_1
	v_add_f32_dpp v82, v82, v82 quad_perm:[1,0,3,2] row_mask:0xf bank_mask:0xf bound_ctrl:1
	v_mul_f32_e32 v64, 0xbfb8aa3b, v174
	v_cvt_f32_f16_sdwa v173, v72 dst_sel:DWORD dst_unused:UNUSED_PAD src0_sel:WORD_1
	v_add_f32_dpp v82, v82, v82 quad_perm:[2,3,0,1] row_mask:0xf bank_mask:0xf bound_ctrl:1
	v_cvt_f32_f16_e32 v172, v72
	v_exp_f32_e32 v64, v64
	v_mul_f32_e32 v72, 0xbfb8aa3b, v175
	v_add_f32_dpp v82, v82, v82 row_half_mirror row_mask:0xf bank_mask:0xf bound_ctrl:1
	v_cvt_f32_f16_sdwa v171, v76 dst_sel:DWORD dst_unused:UNUSED_PAD src0_sel:WORD_1
	v_cvt_f32_f16_e32 v170, v76
	v_exp_f32_e32 v72, v72
	v_pk_add_f32 v[136:137], v[142:143], v[150:151] neg_lo:[0,1] neg_hi:[0,1]
	v_pk_add_f32 v[142:143], v[134:135], v[150:151] neg_lo:[0,1] neg_hi:[0,1]
	v_mul_f32_e32 v82, 0x3c800000, v82
	v_cvt_f32_f16_sdwa v81, v102 dst_sel:DWORD dst_unused:UNUSED_PAD src0_sel:WORD_1
	v_cvt_f32_f16_e32 v80, v102
	s_waitcnt vmcnt(6)
; __device__ __forceinline__ float silu_f(float x) { return x * __builtin_amdgcn_rcpf(1.f + __expf(-x)); }
; __device__ __forceinline__ void phase_post(const Params& p) {
;     ...
;             for (int e = 0; e < 8; ++e) { y[e] = (float)y0[u][e] + (float)y1[u][e]; s += y[e]; }
;             const float mean = red8(s) * (1.f / 64.f); float q = 0.f;
; #pragma unroll
;             for (int e = 0; e < 8; ++e) { y[e] -= mean; q += y[e] * y[e]; }
;             const float rs = rsqrtf(red8(q) * (1.f / 64.f) + 64e-5f);
;             h16x8 o;
; #pragma unroll
;             for (int e = 0; e < 8; ++e) { const float vv = (float)vr[u + 1][e];
;                 const float m0 = e < 4 ? ma0[e & 3] : ma1[e & 3], m1 = e < 4 ? mb0[e & 3] : mb1[e & 3], gg = e < 4 ? lg0[e & 3] : lg1[e & 3], bb = e < 4 ? lb0[e & 3] : lb1[e & 3];
;                 const float vd0 = vv + m0 * ((float)vr[u][e] - vv), vd1 = vv + m1 * ((float)vr[u + 2][e] - vv);
;                 const float val = y[e] * rs * gg + bb + s0[u] * vd0 + s1[u] * vd1;
;                 o[e] = (h16)(val * silu_f((float)zc[u][e])); }
	v_pk_fma_f32 v[140:141], v[142:143], v[40:41], v[150:151]
	v_pk_add_f32 v[142:143], v[156:157], v[152:153] neg_lo:[0,1] neg_hi:[0,1]
	v_cvt_f32_f16_sdwa v89, v87 dst_sel:DWORD dst_unused:UNUSED_PAD src0_sel:WORD_1
	v_cvt_f32_f16_e32 v88, v87
	v_cvt_f32_f16_sdwa v87, v103 dst_sel:DWORD dst_unused:UNUSED_PAD src0_sel:WORD_1
	v_cvt_f32_f16_e32 v86, v103
	v_pk_add_f32 v[154:155], v[158:159], v[82:83] op_sel_hi:[1,0] neg_lo:[0,1] neg_hi:[0,1]
	v_pk_add_f32 v[102:103], v[160:161], v[82:83] op_sel_hi:[1,0] neg_lo:[0,1] neg_hi:[0,1]
	v_pk_add_f32 v[90:91], v[164:165], v[82:83] op_sel_hi:[1,0] neg_lo:[0,1] neg_hi:[0,1]
	v_pk_add_f32 v[94:95], v[94:95], v[82:83] op_sel_hi:[1,0] neg_lo:[0,1] neg_hi:[0,1]
	v_mul_f32_e32 v82, 0xbfb8aa3b, v98
	v_cvt_f32_f16_sdwa v157, v83 dst_sel:DWORD dst_unused:UNUSED_PAD src0_sel:WORD_1
	v_cvt_f32_f16_e32 v156, v83
	v_mul_f32_e32 v83, 0xbfb8aa3b, v99
	v_exp_f32_e32 v82, v82
	v_exp_f32_e32 v83, v83
	v_add_f32_e32 v64, 1.0, v64
	v_pk_add_f32 v[170:171], v[170:171], v[172:173]
	v_rcp_f32_e32 v172, v64
	v_add_f32_e32 v64, 1.0, v72
	v_rcp_f32_e32 v173, v64
	v_add_f32_e32 v82, 1.0, v82
	v_add_f32_e32 v83, 1.0, v83
	v_rcp_f32_e32 v82, v82
	v_rcp_f32_e32 v83, v83
	v_pk_mul_f32 v[172:173], v[172:173], v[174:175]
	v_cvt_f32_f16_sdwa v175, v77 dst_sel:DWORD dst_unused:UNUSED_PAD src0_sel:WORD_1
	v_cvt_f32_f16_e32 v174, v77
	v_cvt_f32_f16_sdwa v77, v73 dst_sel:DWORD dst_unused:UNUSED_PAD src0_sel:WORD_1
	v_cvt_f32_f16_e32 v76, v73
	v_cvt_f32_f16_e32 v64, v65
	v_cvt_f32_f16_sdwa v65, v65 dst_sel:DWORD dst_unused:UNUSED_PAD src0_sel:WORD_1
	v_pk_mul_f32 v[98:99], v[82:83], v[98:99]
	v_cvt_f32_f16_sdwa v83, v68 dst_sel:DWORD dst_unused:UNUSED_PAD src0_sel:WORD_1
	v_cvt_f32_f16_e32 v82, v68
	v_add_f32_e32 v68, 0, v170
	v_add_f32_e32 v68, v171, v68
	v_pk_add_f32 v[76:77], v[174:175], v[76:77]
	v_cvt_f32_f16_sdwa v73, v69 dst_sel:DWORD dst_unused:UNUSED_PAD src0_sel:WORD_1
	v_add_f32_e32 v68, v76, v68
	v_cvt_f32_f16_e32 v72, v69
	v_mul_f32_e32 v69, 0xbfb8aa3b, v64
	v_add_f32_e32 v104, v77, v68
	v_mul_f32_e32 v68, 0xbfb8aa3b, v65
	v_exp_f32_e32 v69, v69
	v_exp_f32_e32 v113, v68
	v_cvt_f32_f16_e32 v182, v66
	v_cvt_f32_f16_sdwa v183, v66 dst_sel:DWORD dst_unused:UNUSED_PAD src0_sel:WORD_1
	v_add_f32_e32 v68, 1.0, v69
	v_add_f32_e32 v69, 1.0, v113
	v_rcp_f32_e32 v68, v68
	v_rcp_f32_e32 v69, v69
	v_cvt_f32_f16_sdwa v181, v74 dst_sel:DWORD dst_unused:UNUSED_PAD src0_sel:WORD_1
	v_cvt_f32_f16_e32 v180, v74
	v_cvt_f32_f16_sdwa v185, v79 dst_sel:DWORD dst_unused:UNUSED_PAD src0_sel:WORD_1
	v_pk_mul_f32 v[178:179], v[68:69], v[64:65]
	v_cvt_f32_f16_sdwa v69, v70 dst_sel:DWORD dst_unused:UNUSED_PAD src0_sel:WORD_1
	v_cvt_f32_f16_e32 v68, v70
	v_mul_f32_e32 v70, 0xbfb8aa3b, v182
	v_exp_f32_e32 v70, v70
	v_cvt_f32_f16_sdwa v65, v78 dst_sel:DWORD dst_unused:UNUSED_PAD src0_sel:WORD_1
	v_cvt_f32_f16_e32 v64, v78
	v_cvt_f32_f16_e32 v184, v79
	v_add_f32_e32 v66, 1.0, v70
	v_rcp_f32_e32 v78, v66
	v_mul_f32_e32 v66, 0xbfb8aa3b, v183
	v_exp_f32_e32 v66, v66
	v_cvt_f32_f16_sdwa v187, v75 dst_sel:DWORD dst_unused:UNUSED_PAD src0_sel:WORD_1
	v_cvt_f32_f16_e32 v186, v75
	v_pk_add_f32 v[64:65], v[64:65], v[180:181]
	v_add_f32_e32 v66, 1.0, v66
	v_add_f32_e32 v74, v64, v104
	v_add_f32_e32 v104, v65, v74
	v_pk_add_f32 v[74:75], v[184:185], v[186:187]
	v_rcp_f32_e32 v79, v66
	v_add_f32_e32 v66, v74, v104
	v_add_f32_e32 v66, v75, v66
	v_pk_add_f32 v[162:163], v[84:85], v[148:149] neg_lo:[0,1] neg_hi:[0,1]
	v_pk_fma_f32 v[138:139], v[136:137], v[44:45], v[150:151]
	v_add_f32_dpp v66, v66, v66 quad_perm:[1,0,3,2] row_mask:0xf bank_mask:0xf bound_ctrl:1
	v_pk_fma_f32 v[136:137], v[162:163], v[42:43], v[148:149]
	v_pk_mul_f32 v[162:163], v[154:155], v[154:155]
	v_add_f32_dpp v66, v66, v66 quad_perm:[2,3,0,1] row_mask:0xf bank_mask:0xf bound_ctrl:1
	v_mov_b32_e32 v187, v162
	v_pk_mul_f32 v[160:161], v[102:103], v[102:103]
	v_add_f32_dpp v66, v66, v66 row_half_mirror row_mask:0xf bank_mask:0xf bound_ctrl:1
	v_mul_f32_e32 v66, 0x3c800000, v66
	v_pk_add_f32 v[170:171], v[170:171], v[66:67] op_sel_hi:[1,0] neg_lo:[0,1] neg_hi:[0,1]
	v_mov_b32_e32 v191, v160
	v_pk_mul_f32 v[184:185], v[170:171], v[170:171]
	v_pk_mul_f32 v[164:165], v[90:91], v[90:91]
	v_mov_b32_e32 v186, v184
	v_mov_b32_e32 v162, v185
	v_pk_add_f32 v[184:185], v[76:77], v[66:67] op_sel_hi:[1,0] neg_lo:[0,1] neg_hi:[0,1]
	v_pk_add_f32 v[162:163], v[186:187], v[162:163]
	v_pk_mul_f32 v[76:77], v[184:185], v[184:185]
	v_pk_add_f32 v[186:187], v[64:65], v[66:67] op_sel_hi:[1,0] neg_lo:[0,1] neg_hi:[0,1]
	v_mov_b32_e32 v190, v76
	v_pk_mul_f32 v[64:65], v[186:187], v[186:187]
	v_pk_add_f32 v[162:163], v[190:191], v[162:163]
	v_mov_b32_e32 v160, v77
	v_pk_add_f32 v[188:189], v[74:75], v[66:67] op_sel_hi:[1,0] neg_lo:[0,1] neg_hi:[0,1]
	v_pk_add_f32 v[76:77], v[160:161], v[162:163]
	v_mov_b32_e32 v160, v64
	v_mov_b32_e32 v161, v164
	v_pk_mul_f32 v[166:167], v[94:95], v[94:95]
	v_pk_mul_f32 v[74:75], v[188:189], v[188:189]
	v_pk_add_f32 v[76:77], v[160:161], v[76:77]
	v_mov_b32_e32 v164, v65
	v_pk_add_f32 v[64:65], v[164:165], v[76:77]
	v_mov_b32_e32 v76, v74
	v_mov_b32_e32 v77, v166
	v_pk_add_f32 v[64:65], v[76:77], v[64:65]
	v_mov_b32_e32 v166, v75
	v_pk_add_f32 v[64:65], v[166:167], v[64:65]
	v_mov_b32_e32 v75, v105
	v_mov_b32_e32 v74, v105
	v_pk_fma_f32 v[100:101], v[100:101], v[46:47], v[148:149]
	v_mov_b32_dpp v75, v65 quad_perm:[1,0,3,2] row_mask:0xf bank_mask:0xf
	v_mov_b32_dpp v74, v64 quad_perm:[1,0,3,2] row_mask:0xf bank_mask:0xf
	v_pk_add_f32 v[64:65], v[64:65], v[74:75]
	v_mov_b32_e32 v75, v105
	v_mov_b32_e32 v74, v105
	s_waitcnt vmcnt(5)
; __device__ __forceinline__ float silu_f(float x) { return x * __builtin_amdgcn_rcpf(1.f + __expf(-x)); }
; __device__ __forceinline__ void phase_post(const Params& p) {
;     ...
;             const float rs = rsqrtf(red8(q) * (1.f / 64.f) + 64e-5f);
;             h16x8 o;
; #pragma unroll
;             for (int e = 0; e < 8; ++e) { const float vv = (float)vr[u + 1][e];
;                 const float m0 = e < 4 ? ma0[e & 3] : ma1[e & 3], m1 = e < 4 ? mb0[e & 3] : mb1[e & 3], gg = e < 4 ? lg0[e & 3] : lg1[e & 3], bb = e < 4 ? lb0[e & 3] : lb1[e & 3];
;                 const float vd0 = vv + m0 * ((float)vr[u][e] - vv), vd1 = vv + m1 * ((float)vr[u + 2][e] - vv);
;                 const float val = y[e] * rs * gg + bb + s0[u] * vd0 + s1[u] * vd1;
;                 o[e] = (h16)(val * silu_f((float)zc[u][e])); }
;             *(h16x8*)(ZCD + (size_t)(tb + u) * 1536 + c) = o; }
	v_pk_fma_f32 v[142:143], v[142:143], v[12:13], v[152:153]
	v_mov_b32_dpp v75, v65 quad_perm:[2,3,0,1] row_mask:0xf bank_mask:0xf
	v_mov_b32_dpp v74, v64 quad_perm:[2,3,0,1] row_mask:0xf bank_mask:0xf
	v_pk_add_f32 v[64:65], v[64:65], v[74:75]
	v_mov_b32_e32 v75, v105
	v_mov_b32_e32 v74, v105
	v_pk_add_f32 v[144:145], v[80:81], v[152:153] neg_lo:[0,1] neg_hi:[0,1]
	v_mov_b32_dpp v75, v65 row_half_mirror row_mask:0xf bank_mask:0xf
	v_mov_b32_dpp v74, v64 row_half_mirror row_mask:0xf bank_mask:0xf
	v_pk_add_f32 v[64:65], v[64:65], v[74:75]
	v_mov_b64_e32 v[74:75], s[28:29]
	v_pk_fma_f32 v[160:161], v[64:65], s[26:27], v[74:75] op_sel_hi:[1,0,0]
	v_cvt_f32_f16_sdwa v65, v71 dst_sel:DWORD dst_unused:UNUSED_PAD src0_sel:WORD_1
	v_mul_f32_e32 v64, 0x4b800000, v161
	v_cmp_gt_f32_e32 vcc, s39, v161
	s_waitcnt vmcnt(4)
	v_pk_fma_f32 v[144:145], v[144:145], v[8:9], v[152:153]
	v_pk_mul_f32 v[162:163], v[78:79], v[182:183]
	v_cndmask_b32_e32 v64, v161, v64, vcc
	v_rsq_f32_e32 v66, v64
	v_cvt_f32_f16_e32 v64, v71
	v_pk_add_f32 v[156:157], v[156:157], v[88:89] neg_lo:[0,1] neg_hi:[0,1]
	v_pk_add_f32 v[158:159], v[86:87], v[88:89] neg_lo:[0,1] neg_hi:[0,1]
	v_mul_f32_e32 v70, 0x45800000, v66
	v_cndmask_b32_e32 v66, v66, v70, vcc
	v_pk_mul_f32 v[70:71], v[154:155], v[66:67] op_sel_hi:[1,0]
	v_cmp_gt_f32_e32 vcc, s39, v160
	s_waitcnt vmcnt(0)
	v_pk_fma_f32 v[70:71], v[32:33], v[70:71], v[36:37]
	v_pk_fma_f32 v[156:157], v[156:157], v[14:15], v[88:89]
	v_pk_fma_f32 v[70:71], v[128:129], v[138:139], v[70:71] op_sel_hi:[0,1,1]
	v_pk_fma_f32 v[70:71], v[132:133], v[140:141], v[70:71] op_sel_hi:[0,1,1]
	v_pk_mul_f32 v[70:71], v[96:97], v[70:71]
	v_pk_fma_f32 v[158:159], v[158:159], v[10:11], v[88:89]
	v_cvt_pk_f16_f32 v76, v70, v71
	v_pk_mul_f32 v[70:71], v[102:103], v[66:67] op_sel_hi:[1,0]
	v_pk_add_f32 v[150:151], v[150:151], v[134:135] neg_lo:[0,1] neg_hi:[0,1]
	v_pk_fma_f32 v[70:71], v[34:35], v[70:71], v[38:39]
	v_pk_fma_f32 v[150:151], v[150:151], v[44:45], v[134:135]
	v_pk_fma_f32 v[70:71], v[128:129], v[100:101], v[70:71] op_sel_hi:[0,1,1]
	v_pk_fma_f32 v[70:71], v[132:133], v[136:137], v[70:71] op_sel_hi:[0,1,1]
	v_pk_mul_f32 v[70:71], v[92:93], v[70:71]
	v_pk_add_f32 v[176:177], v[82:83], v[134:135] neg_lo:[0,1] neg_hi:[0,1]
	v_cvt_pk_f16_f32 v77, v70, v71
	v_pk_mul_f32 v[70:71], v[90:91], v[66:67] op_sel_hi:[1,0]
	v_pk_fma_f32 v[176:177], v[176:177], v[40:41], v[134:135]
	v_pk_fma_f32 v[70:71], v[24:25], v[70:71], v[28:29]
	v_pk_add_f32 v[148:149], v[148:149], v[84:85] neg_lo:[0,1] neg_hi:[0,1]
	v_pk_fma_f32 v[70:71], v[128:129], v[142:143], v[70:71] op_sel_hi:[0,1,1]
	v_pk_fma_f32 v[70:71], v[132:133], v[144:145], v[70:71] op_sel_hi:[0,1,1]
	v_pk_mul_f32 v[70:71], v[146:147], v[70:71]
	v_cvt_f32_f16_e32 v90, v67
	v_cvt_pk_f16_f32 v78, v70, v71
	v_pk_mul_f32 v[70:71], v[94:95], v[66:67] op_sel_hi:[1,0]
	v_mul_f32_e32 v66, 0x4b800000, v160
	v_cndmask_b32_e32 v66, v160, v66, vcc
	v_pk_fma_f32 v[70:71], v[26:27], v[70:71], v[30:31]
	v_rsq_f32_e32 v66, v66
	v_pk_fma_f32 v[70:71], v[128:129], v[156:157], v[70:71] op_sel_hi:[0,1,1]
	v_pk_fma_f32 v[70:71], v[132:133], v[158:159], v[70:71] op_sel_hi:[0,1,1]
	v_pk_mul_f32 v[70:71], v[98:99], v[70:71]
	v_pk_fma_f32 v[148:149], v[148:149], v[46:47], v[84:85]
	v_cvt_pk_f16_f32 v79, v70, v71
	v_mul_f32_e32 v70, 0x45800000, v66
	v_cndmask_b32_e32 v66, v66, v70, vcc
	v_pk_mul_f32 v[70:71], v[170:171], v[66:67] op_sel_hi:[1,0]
	global_store_dwordx4 v[126:127], v[76:79], off sc1
	v_pk_fma_f32 v[70:71], v[32:33], v[70:71], v[36:37]
	v_pk_add_f32 v[174:175], v[72:73], v[84:85] neg_lo:[0,1] neg_hi:[0,1]
	v_pk_fma_f32 v[70:71], v[122:123], v[150:151], v[70:71] op_sel_hi:[0,1,1]
	v_pk_fma_f32 v[70:71], v[124:125], v[176:177], v[70:71] op_sel_hi:[0,1,1]
	v_pk_mul_f32 v[70:71], v[172:173], v[70:71]
	v_pk_fma_f32 v[174:175], v[174:175], v[42:43], v[84:85]
	v_cvt_pk_f16_f32 v76, v70, v71
	v_pk_mul_f32 v[70:71], v[184:185], v[66:67] op_sel_hi:[1,0]
	v_mul_f32_e32 v78, 0xbfb8aa3b, v90
	v_pk_fma_f32 v[70:71], v[34:35], v[70:71], v[38:39]
	v_pk_add_f32 v[152:153], v[152:153], v[80:81] neg_lo:[0,1] neg_hi:[0,1]
	v_pk_fma_f32 v[70:71], v[122:123], v[148:149], v[70:71] op_sel_hi:[0,1,1]
	v_pk_fma_f32 v[70:71], v[124:125], v[174:175], v[70:71] op_sel_hi:[0,1,1]
	v_pk_mul_f32 v[70:71], v[178:179], v[70:71]
	v_exp_f32_e32 v79, v78
	v_cvt_pk_f16_f32 v77, v70, v71
	v_pk_mul_f32 v[70:71], v[186:187], v[66:67] op_sel_hi:[1,0]
	v_pk_fma_f32 v[152:153], v[152:153], v[12:13], v[80:81]
	v_pk_add_f32 v[180:181], v[68:69], v[80:81] neg_lo:[0,1] neg_hi:[0,1]
	v_pk_fma_f32 v[70:71], v[24:25], v[70:71], v[28:29]
	v_cvt_f32_f16_sdwa v91, v67 dst_sel:DWORD dst_unused:UNUSED_PAD src0_sel:WORD_1
	v_pk_fma_f32 v[180:181], v[180:181], v[8:9], v[80:81]
	v_pk_fma_f32 v[70:71], v[122:123], v[152:153], v[70:71] op_sel_hi:[0,1,1]
	v_pk_fma_f32 v[70:71], v[124:125], v[180:181], v[70:71] op_sel_hi:[0,1,1]
	v_pk_mul_f32 v[70:71], v[162:163], v[70:71]
	v_add_f32_e32 v67, 1.0, v79
	v_cvt_pk_f16_f32 v78, v70, v71
	v_rcp_f32_e32 v70, v67
	v_mul_f32_e32 v67, 0xbfb8aa3b, v91
	v_exp_f32_e32 v71, v67
	v_pk_add_f32 v[88:89], v[88:89], v[86:87] neg_lo:[0,1] neg_hi:[0,1]
	v_pk_mul_f32 v[66:67], v[188:189], v[66:67] op_sel_hi:[1,0]
	v_pk_fma_f32 v[88:89], v[88:89], v[14:15], v[86:87]
	v_add_f32_e32 v71, 1.0, v71
	v_rcp_f32_e32 v71, v71
	v_pk_add_f32 v[92:93], v[64:65], v[86:87] neg_lo:[0,1] neg_hi:[0,1]
	v_pk_fma_f32 v[66:67], v[26:27], v[66:67], v[30:31]
	v_pk_fma_f32 v[92:93], v[92:93], v[10:11], v[86:87]
	v_pk_fma_f32 v[66:67], v[122:123], v[88:89], v[66:67] op_sel_hi:[0,1,1]
	v_pk_fma_f32 v[66:67], v[124:125], v[92:93], v[66:67] op_sel_hi:[0,1,1]
; __device__ __forceinline__ float silu_f(float x) { return x * __builtin_amdgcn_rcpf(1.f + __expf(-x)); }
; __device__ __forceinline__ void phase_post(const Params& p) {
;     ...
;             for (int e = 0; e < 8; ++e) { y[e] = (float)y0[u][e] + (float)y1[u][e]; s += y[e]; }
;             const float mean = red8(s) * (1.f / 64.f); float q = 0.f;
;     ...
;                 o[e] = (h16)(val * silu_f((float)zc[u][e])); }
;             *(h16x8*)(ZCD + (size_t)(tb + u) * 1536 + c) = o; }
	v_pk_mul_f32 v[70:71], v[70:71], v[90:91]
	v_cvt_f32_f16_sdwa v93, v60 dst_sel:DWORD dst_unused:UNUSED_PAD src0_sel:WORD_1
	v_pk_mul_f32 v[66:67], v[70:71], v[66:67]
	v_cvt_f32_f16_sdwa v71, v52 dst_sel:DWORD dst_unused:UNUSED_PAD src0_sel:WORD_1
	v_cvt_pk_f16_f32 v79, v66, v67
	global_store_dwordx4 v[120:121], v[76:79], off sc1
	v_cvt_f32_f16_sdwa v67, v56 dst_sel:DWORD dst_unused:UNUSED_PAD src0_sel:WORD_1
	v_cvt_f32_f16_e32 v66, v56
	v_cvt_f32_f16_e32 v76, v48
	v_cvt_f32_f16_sdwa v77, v48 dst_sel:DWORD dst_unused:UNUSED_PAD src0_sel:WORD_1
	v_cvt_f32_f16_e32 v70, v52
	v_cvt_f32_f16_e32 v92, v60
	v_mul_f32_e32 v48, 0xbfb8aa3b, v76
	v_exp_f32_e32 v48, v48
	v_mul_f32_e32 v56, 0xbfb8aa3b, v77
	v_exp_f32_e32 v56, v56
	v_pk_add_f32 v[88:89], v[66:67], v[70:71]
	v_add_f32_e32 v48, 1.0, v48
	v_rcp_f32_e32 v78, v48
	v_add_f32_e32 v48, 1.0, v56
	v_rcp_f32_e32 v79, v48
	v_cvt_f32_f16_e32 v56, v53
	v_cvt_f32_f16_e32 v48, v49
	v_cvt_f32_f16_sdwa v49, v49 dst_sel:DWORD dst_unused:UNUSED_PAD src0_sel:WORD_1
	v_pk_mul_f32 v[76:77], v[78:79], v[76:77]
	v_cvt_f32_f16_sdwa v79, v57 dst_sel:DWORD dst_unused:UNUSED_PAD src0_sel:WORD_1
	v_cvt_f32_f16_e32 v78, v57
	v_cvt_f32_f16_sdwa v57, v53 dst_sel:DWORD dst_unused:UNUSED_PAD src0_sel:WORD_1
	v_add_f32_e32 v52, 0, v88
	v_add_f32_e32 v52, v89, v52
	v_mul_f32_e32 v53, 0xbfb8aa3b, v48
	v_pk_add_f32 v[96:97], v[78:79], v[56:57]
	v_exp_f32_e32 v53, v53
	v_add_f32_e32 v52, v96, v52
	v_add_f32_e32 v91, v97, v52
	v_mul_f32_e32 v52, 0xbfb8aa3b, v49
	v_exp_f32_e32 v56, v52
	v_add_f32_e32 v52, 1.0, v53
	v_cvt_f32_f16_sdwa v95, v61 dst_sel:DWORD dst_unused:UNUSED_PAD src0_sel:WORD_1
	v_cvt_f32_f16_e32 v94, v61
	v_add_f32_e32 v56, 1.0, v56
	v_rcp_f32_e32 v60, v52
	v_rcp_f32_e32 v61, v56
	v_cvt_f32_f16_sdwa v79, v54 dst_sel:DWORD dst_unused:UNUSED_PAD src0_sel:WORD_1
	v_cvt_f32_f16_e32 v78, v54
	v_cvt_f32_f16_sdwa v101, v59 dst_sel:DWORD dst_unused:UNUSED_PAD src0_sel:WORD_1
	v_pk_mul_f32 v[60:61], v[60:61], v[48:49]
	v_cvt_f32_f16_sdwa v49, v58 dst_sel:DWORD dst_unused:UNUSED_PAD src0_sel:WORD_1
	v_cvt_f32_f16_e32 v48, v58
	v_cvt_f32_f16_e32 v100, v59
	v_cvt_f32_f16_sdwa v59, v55 dst_sel:DWORD dst_unused:UNUSED_PAD src0_sel:WORD_1
	v_cvt_f32_f16_e32 v58, v55
	v_pk_add_f32 v[98:99], v[48:49], v[78:79]
	v_cvt_f32_f16_e32 v90, v50
	v_add_f32_e32 v49, v98, v91
	v_cvt_f32_f16_sdwa v91, v50 dst_sel:DWORD dst_unused:UNUSED_PAD src0_sel:WORD_1
	v_pk_add_f32 v[52:53], v[84:85], v[72:73] neg_lo:[0,1] neg_hi:[0,1]
	v_cvt_f32_f16_sdwa v85, v62 dst_sel:DWORD dst_unused:UNUSED_PAD src0_sel:WORD_1
	v_cvt_f32_f16_e32 v84, v62
	v_add_f32_e32 v62, v99, v49
	v_pk_add_f32 v[100:101], v[100:101], v[58:59]
	v_mul_f32_e32 v48, 0xbfb8aa3b, v90
	v_mul_f32_e32 v49, 0xbfb8aa3b, v91
	v_add_f32_e32 v50, v100, v62
	v_exp_f32_e32 v48, v48
	v_exp_f32_e32 v49, v49
	v_add_f32_e32 v50, v101, v50
	v_cvt_f32_f16_e32 v128, v0
	v_add_f32_e32 v48, 1.0, v48
	v_add_f32_dpp v50, v50, v50 quad_perm:[1,0,3,2] row_mask:0xf bank_mask:0xf bound_ctrl:1
	v_add_f32_e32 v49, 1.0, v49
	v_rcp_f32_e32 v48, v48
	v_add_f32_dpp v50, v50, v50 quad_perm:[2,3,0,1] row_mask:0xf bank_mask:0xf bound_ctrl:1
	v_rcp_f32_e32 v49, v49
	v_cvt_f32_f16_sdwa v127, v16 dst_sel:DWORD dst_unused:UNUSED_PAD src0_sel:WORD_1
	v_add_f32_dpp v50, v50, v50 row_half_mirror row_mask:0xf bank_mask:0xf bound_ctrl:1
	v_mul_f32_e32 v50, 0x3c800000, v50
	v_pk_add_f32 v[58:59], v[96:97], v[50:51] op_sel_hi:[1,0] neg_lo:[0,1] neg_hi:[0,1]
	v_cvt_f32_f16_e32 v96, v51
	v_cvt_f32_f16_sdwa v97, v51 dst_sel:DWORD dst_unused:UNUSED_PAD src0_sel:WORD_1
	v_pk_mul_f32 v[54:55], v[48:49], v[90:91]
	v_pk_add_f32 v[90:91], v[88:89], v[50:51] op_sel_hi:[1,0] neg_lo:[0,1] neg_hi:[0,1]
	v_mul_f32_e32 v88, 0xbfb8aa3b, v96
	v_exp_f32_e32 v104, v88
	v_pk_add_f32 v[88:89], v[100:101], v[50:51] op_sel_hi:[1,0] neg_lo:[0,1] neg_hi:[0,1]
	v_mul_f32_e32 v101, 0xbfb8aa3b, v97
	v_exp_f32_e32 v101, v101
	v_cvt_f32_f16_e32 v126, v16
	v_mul_f32_e32 v16, 0xbfb8aa3b, v128
	v_add_f32_e32 v100, 1.0, v104
	v_add_f32_e32 v101, 1.0, v101
	v_exp_f32_e32 v16, v16
	v_rcp_f32_e32 v100, v100
	v_rcp_f32_e32 v101, v101
	v_cvt_f32_f16_sdwa v125, v20 dst_sel:DWORD dst_unused:UNUSED_PAD src0_sel:WORD_1
	v_cvt_f32_f16_e32 v124, v20
	v_cvt_f32_f16_sdwa v129, v0 dst_sel:DWORD dst_unused:UNUSED_PAD src0_sel:WORD_1
	v_add_f32_e32 v0, 1.0, v16
	v_pk_mul_f32 v[96:97], v[100:101], v[96:97]
	v_pk_add_f32 v[100:101], v[124:125], v[126:127]
	v_rcp_f32_e32 v124, v0
	v_cvt_f32_f16_sdwa v127, v4 dst_sel:DWORD dst_unused:UNUSED_PAD src0_sel:WORD_1
	v_cvt_f32_f16_e32 v126, v4
	v_mul_f32_e32 v0, 0xbfb8aa3b, v129
	v_exp_f32_e32 v0, v0
	v_pk_add_f32 v[66:67], v[134:135], v[82:83] neg_lo:[0,1] neg_hi:[0,1]
	v_pk_add_f32 v[70:71], v[92:93], v[82:83] neg_lo:[0,1] neg_hi:[0,1]
	v_pk_fma_f32 v[66:67], v[66:67], v[44:45], v[82:83]
	v_pk_fma_f32 v[70:71], v[70:71], v[40:41], v[82:83]
	v_add_f32_e32 v20, 0, v100
	v_pk_add_f32 v[82:83], v[82:83], v[92:93] neg_lo:[0,1] neg_hi:[0,1]
	v_add_f32_e32 v104, v101, v20
	v_pk_fma_f32 v[44:45], v[82:83], v[44:45], v[92:93]
	v_pk_add_f32 v[82:83], v[126:127], v[92:93] neg_lo:[0,1] neg_hi:[0,1]
	v_cvt_f32_f16_sdwa v127, v21 dst_sel:DWORD dst_unused:UNUSED_PAD src0_sel:WORD_1
	v_cvt_f32_f16_e32 v126, v21
	v_cvt_f32_f16_sdwa v21, v17 dst_sel:DWORD dst_unused:UNUSED_PAD src0_sel:WORD_1
	v_cvt_f32_f16_e32 v20, v17
	v_add_f32_e32 v0, 1.0, v0
	v_rcp_f32_e32 v125, v0
	v_cvt_f32_f16_e32 v0, v1
	v_cvt_f32_f16_sdwa v1, v1 dst_sel:DWORD dst_unused:UNUSED_PAD src0_sel:WORD_1
	v_pk_add_f32 v[16:17], v[126:127], v[20:21]
	v_cvt_f32_f16_sdwa v21, v5 dst_sel:DWORD dst_unused:UNUSED_PAD src0_sel:WORD_1
	v_add_f32_e32 v20, v16, v104
	v_mul_f32_e32 v4, 0xbfb8aa3b, v0
; __device__ __forceinline__ void phase_post(const Params& p) {
;     ...
;             for (int e = 0; e < 8; ++e) { y[e] = (float)y0[u][e] + (float)y1[u][e]; s += y[e]; }
;             const float mean = red8(s) * (1.f / 64.f); float q = 0.f;
; #pragma unroll
;             for (int e = 0; e < 8; ++e) { y[e] -= mean; q += y[e] * y[e]; }
;             const float rs = rsqrtf(red8(q) * (1.f / 64.f) + 64e-5f);
	v_add_f32_e32 v104, v17, v20
	v_cvt_f32_f16_e32 v20, v5
	v_mul_f32_e32 v5, 0xbfb8aa3b, v1
	v_pk_fma_f32 v[40:41], v[82:83], v[40:41], v[92:93]
	v_pk_mul_f32 v[82:83], v[124:125], v[128:129]
	v_exp_f32_e32 v4, v4
	v_exp_f32_e32 v5, v5
	v_cvt_f32_f16_e32 v124, v2
	v_pk_add_f32 v[56:57], v[94:95], v[72:73] neg_lo:[0,1] neg_hi:[0,1]
	v_pk_fma_f32 v[52:53], v[52:53], v[46:47], v[72:73]
	v_pk_fma_f32 v[56:57], v[56:57], v[42:43], v[72:73]
	v_add_f32_e32 v4, 1.0, v4
	v_pk_add_f32 v[72:73], v[72:73], v[94:95] neg_lo:[0,1] neg_hi:[0,1]
	v_add_f32_e32 v5, 1.0, v5
	v_cvt_f32_f16_sdwa v93, v18 dst_sel:DWORD dst_unused:UNUSED_PAD src0_sel:WORD_1
	v_cvt_f32_f16_e32 v92, v18
	v_mul_f32_e32 v18, 0xbfb8aa3b, v124
	v_rcp_f32_e32 v4, v4
	v_pk_fma_f32 v[46:47], v[72:73], v[46:47], v[94:95]
	v_rcp_f32_e32 v5, v5
	v_cvt_f32_f16_sdwa v73, v22 dst_sel:DWORD dst_unused:UNUSED_PAD src0_sel:WORD_1
	v_cvt_f32_f16_e32 v72, v22
	v_exp_f32_e32 v18, v18
	v_cvt_f32_f16_sdwa v125, v2 dst_sel:DWORD dst_unused:UNUSED_PAD src0_sel:WORD_1
	v_pk_mul_f32 v[4:5], v[4:5], v[0:1]
	v_pk_add_f32 v[0:1], v[72:73], v[92:93]
	v_add_f32_e32 v2, 1.0, v18
	v_pk_add_f32 v[78:79], v[80:81], v[68:69] neg_lo:[0,1] neg_hi:[0,1]
	v_pk_add_f32 v[80:81], v[84:85], v[68:69] neg_lo:[0,1] neg_hi:[0,1]
	v_pk_add_f32 v[20:21], v[20:21], v[94:95] neg_lo:[0,1] neg_hi:[0,1]
	v_add_f32_e32 v22, v0, v104
	v_rcp_f32_e32 v18, v2
	v_mul_f32_e32 v2, 0xbfb8aa3b, v125
	v_pk_fma_f32 v[78:79], v[78:79], v[12:13], v[68:69]
	v_pk_fma_f32 v[80:81], v[80:81], v[8:9], v[68:69]
	v_pk_fma_f32 v[20:21], v[20:21], v[42:43], v[94:95]
	v_add_f32_e32 v72, v1, v22
	v_pk_add_f32 v[42:43], v[68:69], v[84:85] neg_lo:[0,1] neg_hi:[0,1]
	v_exp_f32_e32 v2, v2
	v_cvt_f32_f16_sdwa v69, v23 dst_sel:DWORD dst_unused:UNUSED_PAD src0_sel:WORD_1
	v_cvt_f32_f16_e32 v68, v23
	v_cvt_f32_f16_sdwa v23, v19 dst_sel:DWORD dst_unused:UNUSED_PAD src0_sel:WORD_1
	v_cvt_f32_f16_e32 v22, v19
	v_add_f32_e32 v2, 1.0, v2
	v_rcp_f32_e32 v19, v2
	v_pk_mul_f32 v[102:103], v[90:91], v[90:91]
	v_pk_add_f32 v[22:23], v[68:69], v[22:23]
	v_mov_b32_e32 v93, v102
	v_add_f32_e32 v2, v22, v72
	v_add_f32_e32 v2, v23, v2
	v_pk_mul_f32 v[120:121], v[58:59], v[58:59]
	v_cvt_f32_f16_sdwa v49, v63 dst_sel:DWORD dst_unused:UNUSED_PAD src0_sel:WORD_1
	v_add_f32_dpp v2, v2, v2 quad_perm:[1,0,3,2] row_mask:0xf bank_mask:0xf bound_ctrl:1
	v_cvt_f32_f16_e32 v48, v63
	v_pk_add_f32 v[62:63], v[98:99], v[50:51] op_sel_hi:[1,0] neg_lo:[0,1] neg_hi:[0,1]
	v_add_f32_dpp v2, v2, v2 quad_perm:[2,3,0,1] row_mask:0xf bank_mask:0xf bound_ctrl:1
	v_pk_mul_f32 v[98:99], v[62:63], v[62:63]
	v_pk_mul_f32 v[50:51], v[88:89], v[88:89]
	v_add_f32_dpp v2, v2, v2 row_half_mirror row_mask:0xf bank_mask:0xf bound_ctrl:1
	v_mul_f32_e32 v2, 0x3c800000, v2
	v_pk_add_f32 v[68:69], v[100:101], v[2:3] op_sel_hi:[1,0] neg_lo:[0,1] neg_hi:[0,1]
	v_pk_add_f32 v[94:95], v[0:1], v[2:3] op_sel_hi:[1,0] neg_lo:[0,1] neg_hi:[0,1]
	v_pk_mul_f32 v[72:73], v[68:69], v[68:69]
	v_pk_mul_f32 v[0:1], v[94:95], v[94:95]
	v_mov_b32_e32 v92, v72
	v_mov_b32_e32 v102, v73
	v_pk_add_f32 v[72:73], v[92:93], v[102:103]
	v_pk_add_f32 v[92:93], v[16:17], v[2:3] op_sel_hi:[1,0] neg_lo:[0,1] neg_hi:[0,1]
	v_mov_b32_e32 v103, v120
	v_pk_mul_f32 v[16:17], v[92:93], v[92:93]
	v_pk_add_f32 v[22:23], v[22:23], v[2:3] op_sel_hi:[1,0] neg_lo:[0,1] neg_hi:[0,1]
	v_mov_b32_e32 v102, v16
	v_pk_add_f32 v[72:73], v[102:103], v[72:73]
	v_mov_b32_e32 v120, v17
	v_pk_add_f32 v[16:17], v[120:121], v[72:73]
	v_mov_b32_e32 v72, v0
	v_mov_b32_e32 v73, v98
	v_pk_mul_f32 v[100:101], v[22:23], v[22:23]
	v_pk_add_f32 v[16:17], v[72:73], v[16:17]
	v_mov_b32_e32 v98, v1
	v_pk_add_f32 v[0:1], v[98:99], v[16:17]
	v_mov_b32_e32 v16, v100
	v_mov_b32_e32 v17, v50
	v_pk_add_f32 v[0:1], v[16:17], v[0:1]
	v_mov_b32_e32 v50, v101
	v_pk_add_f32 v[0:1], v[50:51], v[0:1]
	v_mov_b32_e32 v17, v105
	v_mov_b32_e32 v16, v105
	v_pk_fma_f32 v[12:13], v[42:43], v[12:13], v[84:85]
	v_mov_b32_dpp v17, v1 quad_perm:[1,0,3,2] row_mask:0xf bank_mask:0xf
	v_mov_b32_dpp v16, v0 quad_perm:[1,0,3,2] row_mask:0xf bank_mask:0xf
	v_pk_add_f32 v[0:1], v[0:1], v[16:17]
	v_mov_b32_e32 v17, v105
	v_mov_b32_e32 v16, v105
	v_cvt_f32_f16_sdwa v43, v6 dst_sel:DWORD dst_unused:UNUSED_PAD src0_sel:WORD_1
	v_mov_b32_dpp v17, v1 quad_perm:[2,3,0,1] row_mask:0xf bank_mask:0xf
	v_mov_b32_dpp v16, v0 quad_perm:[2,3,0,1] row_mask:0xf bank_mask:0xf
	v_pk_add_f32 v[0:1], v[0:1], v[16:17]
	v_mov_b32_e32 v17, v105
	v_mov_b32_e32 v16, v105
	v_cvt_f32_f16_e32 v42, v6
	v_mov_b32_dpp v17, v1 row_half_mirror row_mask:0xf bank_mask:0xf
; __device__ __forceinline__ float silu_f(float x) { return x * __builtin_amdgcn_rcpf(1.f + __expf(-x)); }
; __device__ __forceinline__ void phase_post(const Params& p) {
;     ...
;             const float rs = rsqrtf(red8(q) * (1.f / 64.f) + 64e-5f);
;             h16x8 o;
; #pragma unroll
;             for (int e = 0; e < 8; ++e) { const float vv = (float)vr[u + 1][e];
;                 const float m0 = e < 4 ? ma0[e & 3] : ma1[e & 3], m1 = e < 4 ? mb0[e & 3] : mb1[e & 3], gg = e < 4 ? lg0[e & 3] : lg1[e & 3], bb = e < 4 ? lb0[e & 3] : lb1[e & 3];
;                 const float vd0 = vv + m0 * ((float)vr[u][e] - vv), vd1 = vv + m1 * ((float)vr[u + 2][e] - vv);
;                 const float val = y[e] * rs * gg + bb + s0[u] * vd0 + s1[u] * vd1;
;                 o[e] = (h16)(val * silu_f((float)zc[u][e])); }
;             *(h16x8*)(ZCD + (size_t)(tb + u) * 1536 + c) = o; }
;     }
	v_mov_b32_dpp v16, v0 row_half_mirror row_mask:0xf bank_mask:0xf
	v_pk_add_f32 v[0:1], v[0:1], v[16:17]
	v_pk_add_f32 v[16:17], v[42:43], v[84:85] neg_lo:[0,1] neg_hi:[0,1]
	v_pk_fma_f32 v[0:1], v[0:1], s[26:27], v[74:75] op_sel_hi:[1,0,0]
	v_pk_fma_f32 v[8:9], v[16:17], v[8:9], v[84:85]
	v_mul_f32_e32 v2, 0x4b800000, v1
	v_cmp_gt_f32_e32 vcc, s39, v1
	v_pk_mul_f32 v[42:43], v[18:19], v[124:125]
	v_pk_add_f32 v[86:87], v[86:87], v[64:65] neg_lo:[0,1] neg_hi:[0,1]
	v_cndmask_b32_e32 v1, v1, v2, vcc
	v_rsq_f32_e32 v1, v1
	v_pk_fma_f32 v[86:87], v[86:87], v[14:15], v[64:65]
	v_pk_add_f32 v[122:123], v[48:49], v[64:65] neg_lo:[0,1] neg_hi:[0,1]
	v_add_u32_e32 v168, s27, v168
	v_mul_f32_e32 v2, 0x45800000, v1
	v_cndmask_b32_e32 v2, v1, v2, vcc
	v_pk_mul_f32 v[16:17], v[90:91], v[2:3] op_sel_hi:[1,0]
	v_pk_mul_f32 v[18:19], v[58:59], v[2:3] op_sel_hi:[1,0]
	v_pk_fma_f32 v[16:17], v[32:33], v[16:17], v[36:37]
	v_pk_fma_f32 v[18:19], v[34:35], v[18:19], v[38:39]
	v_pk_fma_f32 v[16:17], v[116:117], v[66:67], v[16:17] op_sel_hi:[0,1,1]
	v_pk_fma_f32 v[18:19], v[116:117], v[52:53], v[18:19] op_sel_hi:[0,1,1]
	v_pk_fma_f32 v[16:17], v[118:119], v[70:71], v[16:17] op_sel_hi:[0,1,1]
	v_pk_fma_f32 v[18:19], v[118:119], v[56:57], v[18:19] op_sel_hi:[0,1,1]
	v_pk_mul_f32 v[16:17], v[76:77], v[16:17]
	v_pk_mul_f32 v[18:19], v[60:61], v[18:19]
	v_mul_f32_e32 v1, 0x4b800000, v0
	v_cmp_gt_f32_e32 vcc, s39, v0
	v_cvt_pk_f16_f32 v16, v16, v17
	v_cvt_pk_f16_f32 v17, v18, v19
	v_pk_mul_f32 v[18:19], v[62:63], v[2:3] op_sel_hi:[1,0]
	v_pk_mul_f32 v[50:51], v[88:89], v[2:3] op_sel_hi:[1,0]
	v_cndmask_b32_e32 v0, v0, v1, vcc
	v_pk_fma_f32 v[18:19], v[24:25], v[18:19], v[28:29]
	v_pk_fma_f32 v[50:51], v[26:27], v[50:51], v[30:31]
	v_rsq_f32_e32 v2, v0
	v_pk_fma_f32 v[122:123], v[122:123], v[10:11], v[64:65]
	v_pk_fma_f32 v[18:19], v[116:117], v[78:79], v[18:19] op_sel_hi:[0,1,1]
	v_pk_fma_f32 v[50:51], v[116:117], v[86:87], v[50:51] op_sel_hi:[0,1,1]
	v_pk_fma_f32 v[18:19], v[118:119], v[80:81], v[18:19] op_sel_hi:[0,1,1]
	v_pk_fma_f32 v[50:51], v[118:119], v[122:123], v[50:51] op_sel_hi:[0,1,1]
	v_pk_mul_f32 v[18:19], v[54:55], v[18:19]
	v_pk_mul_f32 v[0:1], v[96:97], v[50:51]
	v_cvt_pk_f16_f32 v18, v18, v19
	v_cvt_pk_f16_f32 v19, v0, v1
	v_mul_f32_e32 v0, 0x45800000, v2
	v_cndmask_b32_e32 v6, v2, v0, vcc
	global_store_dwordx4 v[114:115], v[16:19], off sc1
	v_pk_mul_f32 v[0:1], v[68:69], v[6:7] op_sel_hi:[1,0]
	v_cmp_lt_i32_e32 vcc, s40, v168
	v_pk_mul_f32 v[16:17], v[92:93], v[6:7] op_sel_hi:[1,0]
	v_pk_fma_f32 v[0:1], v[32:33], v[0:1], v[36:37]
	v_pk_fma_f32 v[16:17], v[34:35], v[16:17], v[38:39]
	v_pk_fma_f32 v[0:1], v[110:111], v[44:45], v[0:1] op_sel_hi:[0,1,1]
	v_pk_fma_f32 v[16:17], v[110:111], v[46:47], v[16:17] op_sel_hi:[0,1,1]
	v_pk_fma_f32 v[16:17], v[112:113], v[20:21], v[16:17] op_sel_hi:[0,1,1]
	v_pk_fma_f32 v[0:1], v[112:113], v[40:41], v[0:1] op_sel_hi:[0,1,1]
	v_pk_mul_f32 v[4:5], v[4:5], v[16:17]
	v_cvt_f32_f16_e32 v16, v3
	v_pk_mul_f32 v[0:1], v[82:83], v[0:1]
	v_cvt_f32_f16_sdwa v17, v3 dst_sel:DWORD dst_unused:UNUSED_PAD src0_sel:WORD_1
	v_cvt_pk_f16_f32 v0, v0, v1
	v_cvt_pk_f16_f32 v1, v4, v5
	v_pk_mul_f32 v[4:5], v[94:95], v[6:7] op_sel_hi:[1,0]
	v_mul_f32_e32 v2, 0xbfb8aa3b, v16
	v_pk_fma_f32 v[4:5], v[24:25], v[4:5], v[28:29]
	s_or_b64 s[24:25], vcc, s[24:25]
	v_pk_fma_f32 v[4:5], v[110:111], v[12:13], v[4:5] op_sel_hi:[0,1,1]
	v_pk_fma_f32 v[4:5], v[112:113], v[8:9], v[4:5] op_sel_hi:[0,1,1]
	v_exp_f32_e32 v8, v2
	v_pk_mul_f32 v[4:5], v[42:43], v[4:5]
	v_cvt_f32_f16_sdwa v13, v7 dst_sel:DWORD dst_unused:UNUSED_PAD src0_sel:WORD_1
	v_cvt_pk_f16_f32 v2, v4, v5
	v_add_f32_e32 v3, 1.0, v8
	v_rcp_f32_e32 v4, v3
	v_mul_f32_e32 v3, 0xbfb8aa3b, v17
	v_exp_f32_e32 v3, v3
	v_cvt_f32_f16_e32 v12, v7
	v_pk_add_f32 v[8:9], v[64:65], v[48:49] neg_lo:[0,1] neg_hi:[0,1]
	v_pk_mul_f32 v[6:7], v[22:23], v[6:7] op_sel_hi:[1,0]
	v_add_f32_e32 v3, 1.0, v3
	v_rcp_f32_e32 v5, v3
	v_pk_fma_f32 v[8:9], v[8:9], v[14:15], v[48:49]
	v_pk_add_f32 v[12:13], v[12:13], v[48:49] neg_lo:[0,1] neg_hi:[0,1]
	v_pk_fma_f32 v[6:7], v[26:27], v[6:7], v[30:31]
	v_pk_fma_f32 v[10:11], v[12:13], v[10:11], v[48:49]
	v_pk_fma_f32 v[6:7], v[110:111], v[8:9], v[6:7] op_sel_hi:[0,1,1]
	v_pk_fma_f32 v[6:7], v[112:113], v[10:11], v[6:7] op_sel_hi:[0,1,1]
	v_pk_mul_f32 v[4:5], v[4:5], v[16:17]
	v_add_u32_e32 v111, s29, v111
	v_pk_mul_f32 v[4:5], v[4:5], v[6:7]
	s_nop 0
	v_cvt_pk_f16_f32 v3, v4, v5
	global_store_dwordx4 v[108:109], v[0:3], off sc1
	s_andn2_b64 exec, exec, s[24:25]
	s_cbranch_execz .LBB0_690

; #define PG8_STAGE(bufoff, gbase, voff) do { _Pragma("unroll") for (int _i = 0; _i < 2; ++_i) \
;         __builtin_amdgcn_global_load_lds((const unsigned*)((const char*)(gbase) + (voff)[_i]), (LAS unsigned*)(lds + (bufoff) + ldsw + _i * 8192), 16, 0, 0); } while (0)
; #define PG8_LDA(dst, b, h) do { _Pragma("unroll") for (int m = 0; m < 4; ++m) _Pragma("unroll") for (int k = 0; k < 2; ++k) dst[m][k] = *(const LAS h16x8*)(lds + PG8_SA(b, h) + aoff + m * 2048 + k * 1024); } while (0)
; #define PG8_LDB(dst, b, h) do { _Pragma("unroll") for (int n = 0; n < 2; ++n) _Pragma("unroll") for (int k = 0; k < 2; ++k) dst[n][k] = *(const LAS h16x8*)(lds + PG8_SB(b, h) + boff + n * 2048 + k * 1024); } while (0)
; #define PG8_MMA(ai, bj, At, Bt) do { __builtin_amdgcn_s_setprio(1); _Pragma("unroll") for (int m = 0; m < 4; ++m) _Pragma("unroll") for (int n = 0; n < 2; ++n) _Pragma("unroll") for (int k = 0; k < 2; ++k) \
;         acc[ai][bj][m][n] = __builtin_amdgcn_mfma_f32_16x16x32_f16(Bt[n][k], At[m][k], acc[ai][bj][m][n], 0, 0, 0); __builtin_amdgcn_s_setprio(0); } while (0)
; #define PG8_WAIT_L(n) asm volatile("s_waitcnt lgkmcnt(" #n ")" ::: "memory")
; #define PG8_BAR __builtin_amdgcn_s_barrier()
; #define PG8_SCHED __builtin_amdgcn_sched_barrier(0)
; template <class Epi>
; __device__ __forceinline__ void gemm_phase(LAS unsigned char* lds, const Gemm g, const StaticOrder& S, const Epi& E) {
;     ...
;             const char* a1 = cA + (size_t)(t + 1) * kstep;
;             const char* a2 = last ? nA : cA + (size_t)(t + 2) * kstep; const char* b2 = last ? nB : cB + (size_t)(t + 2) * kstep;
;             const char* a3 = a2 + kstep; const char* b3 = b2 + kstep;
;             PG8_LDB(B0, 0, 0); PG8_SCHED; PG8_LDA(At, 0, 0); PG8_STAGE(PG8_SA(1, 1), a1 + hstep, voffA);
;             PG8_WAIT_L(8); PG8_BAR; PG8_WAIT_L(0); PG8_MMA(0, 0, At, B0); PG8_BAR; PG8_SCHED;
;             PG8_LDB(B1, 0, 1); PG8_STAGE(PG8_SB(0, 0), b2, voffB);
;             PG8_BAR; PG8_WAIT_L(0); PG8_MMA(0, 1, At, B1); PG8_BAR;
;             PG8_LDA(At, 0, 1); PG8_STAGE(PG8_SA(0, 0), a2, voffA);
;             PG8_BAR; PG8_WAIT_L(0); PG8_MMA(1, 0, At, B0); PG8_BAR; PG8_SCHED;
.LBB0_761:
	ds_read_b128 v[152:155], v149
	ds_read_b128 v[156:159], v149 offset:1024
	ds_read_b128 v[160:163], v149 offset:2048
	ds_read_b128 v[164:167], v149 offset:3072
	s_add_u32 s28, s26, 0xfffa0080
	s_addc_u32 s29, s27, -1
	s_cmp_eq_u32 s15, 20
	s_cselect_b32 s31, s1, s29
	s_cselect_b32 s30, s0, s28
	s_cselect_b32 s29, s5, s14
	s_cselect_b32 s28, s4, s62
	v_lshl_add_u64 v[200:201], s[26:27], 0, v[138:139]
	s_add_i32 m0, s42, 0xc000
	ds_read_b128 v[168:171], v150
	ds_read_b128 v[172:175], v150 offset:1024
	ds_read_b128 v[176:179], v150 offset:2048
	ds_read_b128 v[180:183], v150 offset:3072
	ds_read_b128 v[184:187], v150 offset:4096
	ds_read_b128 v[188:191], v150 offset:5120
	ds_read_b128 v[192:195], v150 offset:6144
	ds_read_b128 v[196:199], v150 offset:7168
	global_load_lds_dwordx4 v[200:201], off
	v_lshl_add_u64 v[200:201], s[26:27], 0, v[140:141]
	s_add_i32 m0, s42, 0xe000
	s_nop 0
	global_load_lds_dwordx4 v[200:201], off
	s_waitcnt lgkmcnt(8)
	s_barrier
	s_waitcnt lgkmcnt(0)
	s_waitcnt lgkmcnt(0)
	v_mfma_f32_16x16x32_f16 v[124:127], v[152:155], v[168:171], v[124:127]
	v_mfma_f32_16x16x32_f16 v[120:123], v[160:163], v[168:171], v[120:123]
	v_mfma_f32_16x16x32_f16 v[116:119], v[152:155], v[176:179], v[116:119]
	v_mfma_f32_16x16x32_f16 v[112:115], v[160:163], v[176:179], v[112:115]
	v_mfma_f32_16x16x32_f16 v[100:103], v[152:155], v[184:187], v[100:103]
	v_mfma_f32_16x16x32_f16 v[96:99], v[160:163], v[184:187], v[96:99]
	v_mfma_f32_16x16x32_f16 v[84:87], v[152:155], v[192:195], v[84:87]
	v_mfma_f32_16x16x32_f16 v[80:83], v[160:163], v[192:195], v[80:83]
	v_mfma_f32_16x16x32_f16 v[124:127], v[156:159], v[172:175], v[124:127]
	v_mfma_f32_16x16x32_f16 v[120:123], v[164:167], v[172:175], v[120:123]
	v_mfma_f32_16x16x32_f16 v[116:119], v[156:159], v[180:183], v[116:119]
	v_mfma_f32_16x16x32_f16 v[112:115], v[164:167], v[180:183], v[112:115]
	v_mfma_f32_16x16x32_f16 v[100:103], v[156:159], v[188:191], v[100:103]
	v_mfma_f32_16x16x32_f16 v[96:99], v[164:167], v[188:191], v[96:99]
	v_mfma_f32_16x16x32_f16 v[84:87], v[156:159], v[196:199], v[84:87]
	v_mfma_f32_16x16x32_f16 v[80:83], v[164:167], v[196:199], v[80:83]
	s_barrier
	s_add_i32 s34, s53, s40
	v_lshl_add_u64 v[216:217], s[28:29], 0, v[132:133]
	s_mov_b32 m0, s34
	ds_read_b128 v[200:203], v151
	ds_read_b128 v[204:207], v151 offset:1024
	ds_read_b128 v[208:211], v151 offset:2048
	ds_read_b128 v[212:215], v151 offset:3072
	global_load_lds_dwordx4 v[216:217], off
	v_lshl_add_u64 v[218:219], s[28:29], 0, v[136:137]
	s_add_i32 m0, s34, 0x2000
	s_nop 0
	global_load_lds_dwordx4 v[218:219], off
	s_barrier
	s_waitcnt lgkmcnt(0)
	s_waitcnt lgkmcnt(0)
	v_mfma_f32_16x16x32_f16 v[108:111], v[200:203], v[168:171], v[108:111]
	v_mfma_f32_16x16x32_f16 v[104:107], v[208:211], v[168:171], v[104:107]
	v_mfma_f32_16x16x32_f16 v[92:95], v[200:203], v[176:179], v[92:95]
	v_mfma_f32_16x16x32_f16 v[88:91], v[208:211], v[176:179], v[88:91]
	v_mfma_f32_16x16x32_f16 v[76:79], v[200:203], v[184:187], v[76:79]
	v_mfma_f32_16x16x32_f16 v[72:75], v[208:211], v[184:187], v[72:75]
	v_mfma_f32_16x16x32_f16 v[68:71], v[200:203], v[192:195], v[68:71]
	v_mfma_f32_16x16x32_f16 v[64:67], v[208:211], v[192:195], v[64:67]
	v_mfma_f32_16x16x32_f16 v[108:111], v[204:207], v[172:175], v[108:111]
	v_mfma_f32_16x16x32_f16 v[104:107], v[212:215], v[172:175], v[104:107]
	v_mfma_f32_16x16x32_f16 v[92:95], v[204:207], v[180:183], v[92:95]
	v_mfma_f32_16x16x32_f16 v[88:91], v[212:215], v[180:183], v[88:91]
	v_mfma_f32_16x16x32_f16 v[76:79], v[204:207], v[188:191], v[76:79]
	v_mfma_f32_16x16x32_f16 v[72:75], v[212:215], v[188:191], v[72:75]
	v_mfma_f32_16x16x32_f16 v[68:71], v[204:207], v[196:199], v[68:71]
	v_mfma_f32_16x16x32_f16 v[64:67], v[212:215], v[196:199], v[64:67]
	s_mov_b32 m0, s42
	v_lshl_add_u64 v[220:221], s[30:31], 0, v[128:129]
	s_barrier
	ds_read_b128 v[168:171], v150 offset:16384
	ds_read_b128 v[172:175], v150 offset:17408
	ds_read_b128 v[176:179], v150 offset:18432
	ds_read_b128 v[180:183], v150 offset:19456
	ds_read_b128 v[184:187], v150 offset:20480
	ds_read_b128 v[188:191], v150 offset:21504
	ds_read_b128 v[192:195], v150 offset:22528
	ds_read_b128 v[196:199], v150 offset:23552
	global_load_lds_dwordx4 v[220:221], off
	v_lshl_add_u64 v[222:223], s[30:31], 0, v[134:135]
	s_mov_b32 m0, s43
	s_nop 0
	global_load_lds_dwordx4 v[222:223], off
	s_barrier
	s_waitcnt lgkmcnt(0)
	s_waitcnt lgkmcnt(0)
	v_mfma_f32_16x16x32_f16 v[60:63], v[152:155], v[168:171], v[60:63]
	v_mfma_f32_16x16x32_f16 v[56:59], v[160:163], v[168:171], v[56:59]
	v_mfma_f32_16x16x32_f16 v[52:55], v[152:155], v[176:179], v[52:55]
	v_mfma_f32_16x16x32_f16 v[48:51], v[160:163], v[176:179], v[48:51]
	v_mfma_f32_16x16x32_f16 v[36:39], v[152:155], v[184:187], v[36:39]
	v_mfma_f32_16x16x32_f16 v[32:35], v[160:163], v[184:187], v[32:35]
	v_mfma_f32_16x16x32_f16 v[20:23], v[152:155], v[192:195], v[20:23]
	v_mfma_f32_16x16x32_f16 v[16:19], v[160:163], v[192:195], v[16:19]
	v_mfma_f32_16x16x32_f16 v[60:63], v[156:159], v[172:175], v[60:63]
	v_mfma_f32_16x16x32_f16 v[56:59], v[164:167], v[172:175], v[56:59]
	v_mfma_f32_16x16x32_f16 v[52:55], v[156:159], v[180:183], v[52:55]
	v_mfma_f32_16x16x32_f16 v[48:51], v[164:167], v[180:183], v[48:51]
	v_mfma_f32_16x16x32_f16 v[36:39], v[156:159], v[188:191], v[36:39]
	v_mfma_f32_16x16x32_f16 v[32:35], v[164:167], v[188:191], v[32:35]
	v_mfma_f32_16x16x32_f16 v[20:23], v[156:159], v[196:199], v[20:23]
	v_mfma_f32_16x16x32_f16 v[16:19], v[164:167], v[196:199], v[16:19]
	s_barrier
; #define PG8_STAGE(bufoff, gbase, voff) do { _Pragma("unroll") for (int _i = 0; _i < 2; ++_i) \
;         __builtin_amdgcn_global_load_lds((const unsigned*)((const char*)(gbase) + (voff)[_i]), (LAS unsigned*)(lds + (bufoff) + ldsw + _i * 8192), 16, 0, 0); } while (0)
; #define PG8_LDA(dst, b, h) do { _Pragma("unroll") for (int m = 0; m < 4; ++m) _Pragma("unroll") for (int k = 0; k < 2; ++k) dst[m][k] = *(const LAS h16x8*)(lds + PG8_SA(b, h) + aoff + m * 2048 + k * 1024); } while (0)
; #define PG8_LDB(dst, b, h) do { _Pragma("unroll") for (int n = 0; n < 2; ++n) _Pragma("unroll") for (int k = 0; k < 2; ++k) dst[n][k] = *(const LAS h16x8*)(lds + PG8_SB(b, h) + boff + n * 2048 + k * 1024); } while (0)
; #define PG8_MMA(ai, bj, At, Bt) do { __builtin_amdgcn_s_setprio(1); _Pragma("unroll") for (int m = 0; m < 4; ++m) _Pragma("unroll") for (int n = 0; n < 2; ++n) _Pragma("unroll") for (int k = 0; k < 2; ++k) \
;         acc[ai][bj][m][n] = __builtin_amdgcn_mfma_f32_16x16x32_f16(Bt[n][k], At[m][k], acc[ai][bj][m][n], 0, 0, 0); __builtin_amdgcn_s_setprio(0); } while (0)
; #define PG8_WAIT_V(n) asm volatile("s_waitcnt vmcnt(" #n ")" ::: "memory")
; #define PG8_WAIT_L(n) asm volatile("s_waitcnt lgkmcnt(" #n ")" ::: "memory")
; #define PG8_BAR __builtin_amdgcn_s_barrier()
; #define PG8_SCHED __builtin_amdgcn_sched_barrier(0)
; template <class Epi>
; __device__ __forceinline__ void gemm_phase(LAS unsigned char* lds, const Gemm g, const StaticOrder& S, const Epi& E) {
;     ...
;             PG8_STAGE(PG8_SB(0, 1), b2 + hstep, voffB);
;             PG8_WAIT_V(6); PG8_BAR; PG8_MMA(1, 1, At, B1); PG8_BAR;
;             PG8_LDB(B0, 1, 0); PG8_SCHED; PG8_LDA(At, 1, 0); PG8_STAGE(PG8_SA(0, 1), a2 + hstep, voffA);
;             PG8_WAIT_L(8); PG8_BAR; PG8_WAIT_L(0); PG8_MMA(0, 0, At, B0); PG8_BAR; PG8_SCHED;
;             PG8_LDB(B1, 1, 1); PG8_STAGE(PG8_SB(1, 0), b3, voffB);
;             PG8_BAR; PG8_WAIT_L(0); PG8_MMA(0, 1, At, B1); PG8_BAR;
	s_add_u32 s34, s28, 0x60000
	s_addc_u32 s35, s29, 0
	s_add_i32 s63, s54, s40
	v_lshl_add_u64 v[152:153], s[34:35], 0, v[132:133]
	s_mov_b32 m0, s63
	s_nop 0
	global_load_lds_dwordx4 v[152:153], off
	v_lshl_add_u64 v[152:153], s[34:35], 0, v[136:137]
	s_add_i32 m0, s63, 0x2000
	s_nop 0
	global_load_lds_dwordx4 v[152:153], off
	s_waitcnt vmcnt(6)
	s_barrier
	v_mfma_f32_16x16x32_f16 v[44:47], v[200:203], v[168:171], v[44:47]
	v_mfma_f32_16x16x32_f16 v[40:43], v[208:211], v[168:171], v[40:43]
	v_mfma_f32_16x16x32_f16 v[28:31], v[200:203], v[176:179], v[28:31]
	v_mfma_f32_16x16x32_f16 v[24:27], v[208:211], v[176:179], v[24:27]
	v_mfma_f32_16x16x32_f16 v[12:15], v[200:203], v[184:187], v[12:15]
	v_mfma_f32_16x16x32_f16 v[8:11], v[208:211], v[184:187], v[8:11]
	v_mfma_f32_16x16x32_f16 v[4:7], v[200:203], v[192:195], v[4:7]
	v_mfma_f32_16x16x32_f16 v[0:3], v[208:211], v[192:195], v[0:3]
	v_mfma_f32_16x16x32_f16 v[44:47], v[204:207], v[172:175], v[44:47]
	v_mfma_f32_16x16x32_f16 v[40:43], v[212:215], v[172:175], v[40:43]
	v_mfma_f32_16x16x32_f16 v[28:31], v[204:207], v[180:183], v[28:31]
	v_mfma_f32_16x16x32_f16 v[24:27], v[212:215], v[180:183], v[24:27]
	v_mfma_f32_16x16x32_f16 v[12:15], v[204:207], v[188:191], v[12:15]
	v_mfma_f32_16x16x32_f16 v[8:11], v[212:215], v[188:191], v[8:11]
	v_mfma_f32_16x16x32_f16 v[4:7], v[204:207], v[196:199], v[4:7]
	v_mfma_f32_16x16x32_f16 v[0:3], v[212:215], v[196:199], v[0:3]
	s_add_i32 s34, 0, 0x18000
	v_add_u32_e32 v164, s34, v147
	s_barrier
	ds_read_b128 v[152:155], v164
	ds_read_b128 v[156:159], v164 offset:1024
	ds_read_b128 v[160:163], v164 offset:2048
	ds_read_b128 v[164:167], v164 offset:3072
	s_add_u32 s30, s30, 0x60000
	s_addc_u32 s31, s31, 0
	s_mov_b32 m0, s44
	v_lshl_add_u64 v[200:201], s[30:31], 0, v[128:129]
	ds_read_b128 v[168:171], v150 offset:32768
	ds_read_b128 v[172:175], v150 offset:33792
	ds_read_b128 v[176:179], v150 offset:34816
	ds_read_b128 v[180:183], v150 offset:35840
	ds_read_b128 v[184:187], v150 offset:36864
	ds_read_b128 v[188:191], v150 offset:37888
	ds_read_b128 v[192:195], v150 offset:38912
	ds_read_b128 v[196:199], v150 offset:39936
	global_load_lds_dwordx4 v[200:201], off
	v_lshl_add_u64 v[200:201], s[30:31], 0, v[134:135]
	s_mov_b32 m0, s45
	s_nop 0
	global_load_lds_dwordx4 v[200:201], off
	s_waitcnt lgkmcnt(8)
	s_barrier
	s_waitcnt lgkmcnt(0)
	s_waitcnt lgkmcnt(0)
	v_mfma_f32_16x16x32_f16 v[124:127], v[152:155], v[168:171], v[124:127]
	v_mfma_f32_16x16x32_f16 v[120:123], v[160:163], v[168:171], v[120:123]
	v_mfma_f32_16x16x32_f16 v[116:119], v[152:155], v[176:179], v[116:119]
	v_mfma_f32_16x16x32_f16 v[112:115], v[160:163], v[176:179], v[112:115]
	v_mfma_f32_16x16x32_f16 v[100:103], v[152:155], v[184:187], v[100:103]
	v_mfma_f32_16x16x32_f16 v[96:99], v[160:163], v[184:187], v[96:99]
	v_mfma_f32_16x16x32_f16 v[84:87], v[152:155], v[192:195], v[84:87]
	v_mfma_f32_16x16x32_f16 v[80:83], v[160:163], v[192:195], v[80:83]
	v_mfma_f32_16x16x32_f16 v[124:127], v[156:159], v[172:175], v[124:127]
	v_mfma_f32_16x16x32_f16 v[120:123], v[164:167], v[172:175], v[120:123]
	v_mfma_f32_16x16x32_f16 v[116:119], v[156:159], v[180:183], v[116:119]
	v_mfma_f32_16x16x32_f16 v[112:115], v[164:167], v[180:183], v[112:115]
	v_mfma_f32_16x16x32_f16 v[100:103], v[156:159], v[188:191], v[100:103]
	v_mfma_f32_16x16x32_f16 v[96:99], v[164:167], v[188:191], v[96:99]
	v_mfma_f32_16x16x32_f16 v[84:87], v[156:159], v[196:199], v[84:87]
	v_mfma_f32_16x16x32_f16 v[80:83], v[164:167], v[196:199], v[80:83]
	s_barrier
	s_add_i32 s30, 0, 0x1c000
	s_add_i32 s31, s34, s40
	v_add_u32_e32 v212, s30, v147
	v_lshl_add_u64 v[216:217], v[216:217], 0, s[12:13]
	s_mov_b32 m0, s31
	ds_read_b128 v[200:203], v212
	ds_read_b128 v[204:207], v212 offset:1024
	ds_read_b128 v[208:211], v212 offset:2048
	ds_read_b128 v[212:215], v212 offset:3072
	global_load_lds_dwordx4 v[216:217], off
	v_lshl_add_u64 v[216:217], v[218:219], 0, s[12:13]
	s_add_i32 m0, s31, 0x2000
	s_nop 0
	global_load_lds_dwordx4 v[216:217], off
	s_barrier
	s_waitcnt lgkmcnt(0)
	s_waitcnt lgkmcnt(0)
	v_mfma_f32_16x16x32_f16 v[108:111], v[200:203], v[168:171], v[108:111]
	v_mfma_f32_16x16x32_f16 v[104:107], v[208:211], v[168:171], v[104:107]
	v_mfma_f32_16x16x32_f16 v[92:95], v[200:203], v[176:179], v[92:95]
	v_mfma_f32_16x16x32_f16 v[88:91], v[208:211], v[176:179], v[88:91]
	v_mfma_f32_16x16x32_f16 v[76:79], v[200:203], v[184:187], v[76:79]
	v_mfma_f32_16x16x32_f16 v[72:75], v[208:211], v[184:187], v[72:75]
	v_mfma_f32_16x16x32_f16 v[68:71], v[200:203], v[192:195], v[68:71]
	v_mfma_f32_16x16x32_f16 v[64:67], v[208:211], v[192:195], v[64:67]
	v_mfma_f32_16x16x32_f16 v[108:111], v[204:207], v[172:175], v[108:111]
	v_mfma_f32_16x16x32_f16 v[104:107], v[212:215], v[172:175], v[104:107]
	v_mfma_f32_16x16x32_f16 v[92:95], v[204:207], v[180:183], v[92:95]
	v_mfma_f32_16x16x32_f16 v[88:91], v[212:215], v[180:183], v[88:91]
	v_mfma_f32_16x16x32_f16 v[76:79], v[204:207], v[188:191], v[76:79]
	v_mfma_f32_16x16x32_f16 v[72:75], v[212:215], v[188:191], v[72:75]
	v_mfma_f32_16x16x32_f16 v[68:71], v[204:207], v[196:199], v[68:71]
	v_mfma_f32_16x16x32_f16 v[64:67], v[212:215], v[196:199], v[64:67]
	s_mov_b32 m0, s48
	v_lshl_add_u64 v[216:217], v[220:221], 0, s[12:13]
	s_barrier
	ds_read_b128 v[168:171], v150 offset:49152
	ds_read_b128 v[172:175], v150 offset:50176
	ds_read_b128 v[176:179], v150 offset:51200
	ds_read_b128 v[180:183], v150 offset:52224
	ds_read_b128 v[184:187], v150 offset:53248
	ds_read_b128 v[188:191], v150 offset:54272
	ds_read_b128 v[192:195], v150 offset:55296
	ds_read_b128 v[196:199], v150 offset:56320
	global_load_lds_dwordx4 v[216:217], off
	v_lshl_add_u64 v[216:217], v[222:223], 0, s[12:13]
	s_mov_b32 m0, s49
	s_nop 0
	global_load_lds_dwordx4 v[216:217], off
	s_barrier
; #define PG8_STAGE(bufoff, gbase, voff) do { _Pragma("unroll") for (int _i = 0; _i < 2; ++_i) \
;         __builtin_amdgcn_global_load_lds((const unsigned*)((const char*)(gbase) + (voff)[_i]), (LAS unsigned*)(lds + (bufoff) + ldsw + _i * 8192), 16, 0, 0); } while (0)
; #define PG8_MMA(ai, bj, At, Bt) do { __builtin_amdgcn_s_setprio(1); _Pragma("unroll") for (int m = 0; m < 4; ++m) _Pragma("unroll") for (int n = 0; n < 2; ++n) _Pragma("unroll") for (int k = 0; k < 2; ++k) \
;         acc[ai][bj][m][n] = __builtin_amdgcn_mfma_f32_16x16x32_f16(Bt[n][k], At[m][k], acc[ai][bj][m][n], 0, 0, 0); __builtin_amdgcn_s_setprio(0); } while (0)
; #define PG8_WAIT_V(n) asm volatile("s_waitcnt vmcnt(" #n ")" ::: "memory")
; #define PG8_WAIT_L(n) asm volatile("s_waitcnt lgkmcnt(" #n ")" ::: "memory")
; #define PG8_BAR __builtin_amdgcn_s_barrier()
; #define PG8_SCHED __builtin_amdgcn_sched_barrier(0)
; template <class Epi>
; __device__ __forceinline__ void gemm_phase(LAS unsigned char* lds, const Gemm g, const StaticOrder& S, const Epi& E) {
;     ...
;             PG8_BAR; PG8_WAIT_L(0); PG8_MMA(1, 0, At, B0); PG8_BAR; PG8_SCHED;
;             PG8_STAGE(PG8_SB(1, 1), b3 + hstep, voffB);
;             PG8_WAIT_V(6); PG8_BAR; PG8_MMA(1, 1, At, B1); PG8_BAR;
	s_waitcnt lgkmcnt(0)
	s_waitcnt lgkmcnt(0)
	v_mfma_f32_16x16x32_f16 v[60:63], v[152:155], v[168:171], v[60:63]
	v_mfma_f32_16x16x32_f16 v[56:59], v[160:163], v[168:171], v[56:59]
	v_mfma_f32_16x16x32_f16 v[52:55], v[152:155], v[176:179], v[52:55]
	v_mfma_f32_16x16x32_f16 v[48:51], v[160:163], v[176:179], v[48:51]
	v_mfma_f32_16x16x32_f16 v[36:39], v[152:155], v[184:187], v[36:39]
	v_mfma_f32_16x16x32_f16 v[32:35], v[160:163], v[184:187], v[32:35]
	v_mfma_f32_16x16x32_f16 v[20:23], v[152:155], v[192:195], v[20:23]
	v_mfma_f32_16x16x32_f16 v[16:19], v[160:163], v[192:195], v[16:19]
	v_mfma_f32_16x16x32_f16 v[60:63], v[156:159], v[172:175], v[60:63]
	v_mfma_f32_16x16x32_f16 v[56:59], v[164:167], v[172:175], v[56:59]
	v_mfma_f32_16x16x32_f16 v[52:55], v[156:159], v[180:183], v[52:55]
	v_mfma_f32_16x16x32_f16 v[48:51], v[164:167], v[180:183], v[48:51]
	v_mfma_f32_16x16x32_f16 v[36:39], v[156:159], v[188:191], v[36:39]
	v_mfma_f32_16x16x32_f16 v[32:35], v[164:167], v[188:191], v[32:35]
	v_mfma_f32_16x16x32_f16 v[20:23], v[156:159], v[196:199], v[20:23]
	v_mfma_f32_16x16x32_f16 v[16:19], v[164:167], v[196:199], v[16:19]
	s_barrier
	s_add_u32 s28, s28, 0x60080
	s_addc_u32 s29, s29, 0
	s_add_i32 s30, s30, s40
	v_lshl_add_u64 v[152:153], s[28:29], 0, v[132:133]
	s_mov_b32 m0, s30
	s_nop 0
	global_load_lds_dwordx4 v[152:153], off
	v_lshl_add_u64 v[152:153], s[28:29], 0, v[136:137]
	s_add_i32 m0, s30, 0x2000
	s_nop 0
	global_load_lds_dwordx4 v[152:153], off
	s_waitcnt vmcnt(6)
	s_barrier
	v_mfma_f32_16x16x32_f16 v[44:47], v[200:203], v[168:171], v[44:47]
	v_mfma_f32_16x16x32_f16 v[40:43], v[208:211], v[168:171], v[40:43]
	v_mfma_f32_16x16x32_f16 v[28:31], v[200:203], v[176:179], v[28:31]
	v_mfma_f32_16x16x32_f16 v[24:27], v[208:211], v[176:179], v[24:27]
	v_mfma_f32_16x16x32_f16 v[12:15], v[200:203], v[184:187], v[12:15]
	v_mfma_f32_16x16x32_f16 v[8:11], v[208:211], v[184:187], v[8:11]
	v_mfma_f32_16x16x32_f16 v[4:7], v[200:203], v[192:195], v[4:7]
	v_mfma_f32_16x16x32_f16 v[0:3], v[208:211], v[192:195], v[0:3]
	v_mfma_f32_16x16x32_f16 v[44:47], v[204:207], v[172:175], v[44:47]
	v_mfma_f32_16x16x32_f16 v[40:43], v[212:215], v[172:175], v[40:43]
	v_mfma_f32_16x16x32_f16 v[28:31], v[204:207], v[180:183], v[28:31]
	v_mfma_f32_16x16x32_f16 v[24:27], v[212:215], v[180:183], v[24:27]
	v_mfma_f32_16x16x32_f16 v[12:15], v[204:207], v[188:191], v[12:15]
	v_mfma_f32_16x16x32_f16 v[8:11], v[212:215], v[188:191], v[8:11]
	v_mfma_f32_16x16x32_f16 v[4:7], v[204:207], v[196:199], v[4:7]
	v_mfma_f32_16x16x32_f16 v[0:3], v[212:215], v[196:199], v[0:3]
	s_add_i32 s15, s15, 2
	s_add_u32 s26, s26, 0x100
	s_addc_u32 s27, s27, 0
	s_add_u32 s62, s62, 0x100
	s_addc_u32 s14, s14, 0
	s_cmp_gt_u32 s15, 21
	s_barrier
	s_cbranch_scc0 .LBB0_761
;     __device__ __forceinline__ void operator()(const f32x4 (&acc)[2][2][4][2], const pg8::Unit& u, int wr, int wc, int fr, int fq) const {
;         const int row0 = u.pm * 256 + wr * 64 + fr, col0 = u.pn * 256 + wc * 32 + 8 * fq;
; #pragma unroll
;         for (int ai = 0; ai < 2; ++ai)
; #pragma unroll
;             for (int m = 0; m < 4; ++m) { const size_t r = (size_t)(row0 + ai * 128 + m * 16);
; #pragma unroll
;                 for (int bj = 0; bj < 2; ++bj) { const f32x4 v0 = acc[ai][bj][m][0], v1 = acc[ai][bj][m][1]; h16x8 o;
; #pragma unroll
;                     for (int e = 0; e < 4; ++e) { o[e] = (h16)v0[e]; o[4 + e] = (h16)v1[e]; }
;                     *(h16x8*)(O2 + r * 1024 + col0 + bj * 128) = o; } }
	v_lshl_add_u32 v152, s58, 8, v146
	v_lshl_or_b32 v154, s61, 8, v148
	v_ashrrev_i32_e32 v153, 31, v152
	v_ashrrev_i32_e32 v155, 31, v154
	v_lshlrev_b64 v[156:157], 11, v[152:153]
	v_cvt_pk_f16_f32 v123, v122, v123
	v_cvt_pk_f16_f32 v122, v120, v121
	v_cvt_pk_f16_f32 v121, v126, v127
	v_cvt_pk_f16_f32 v120, v124, v125
	v_lshl_add_u64 v[124:125], s[10:11], 0, v[156:157]
	v_lshlrev_b64 v[126:127], 1, v[154:155]
	v_lshl_add_u64 v[124:125], v[124:125], 0, v[126:127]
	v_cvt_pk_f16_f32 v107, v106, v107
	v_cvt_pk_f16_f32 v106, v104, v105
	v_cvt_pk_f16_f32 v105, v110, v111
	v_cvt_pk_f16_f32 v104, v108, v109
	global_store_dwordx4 v[124:125], v[104:107], off offset:256 sc1
	v_cvt_pk_f16_f32 v91, v90, v91
	v_cvt_pk_f16_f32 v90, v88, v89
	v_or_b32_e32 v104, 16, v152
	v_ashrrev_i32_e32 v105, 31, v104
	v_lshlrev_b64 v[108:109], 11, v[104:105]
	v_lshl_add_u64 v[108:109], s[10:11], 0, v[108:109]
	v_lshl_add_u64 v[108:109], v[108:109], 0, v[126:127]
	v_cvt_pk_f16_f32 v89, v94, v95
	v_cvt_pk_f16_f32 v88, v92, v93
	global_store_dwordx4 v[108:109], v[88:91], off offset:256 sc1
	v_cvt_pk_f16_f32 v59, v58, v59
	v_cvt_pk_f16_f32 v58, v56, v57
	v_or_b32_e32 v88, 32, v152
	v_ashrrev_i32_e32 v89, 31, v88
	v_cvt_pk_f16_f32 v57, v62, v63
	v_add_co_u32_e32 v62, vcc, s55, v124
	v_lshlrev_b64 v[92:93], 11, v[88:89]
	s_nop 0
	v_addc_co_u32_e32 v63, vcc, 0, v125, vcc
	v_lshl_add_u64 v[92:93], s[10:11], 0, v[92:93]
	v_cvt_pk_f16_f32 v43, v42, v43
	v_cvt_pk_f16_f32 v42, v40, v41
	v_cvt_pk_f16_f32 v41, v46, v47
	v_add_co_u32_e32 v46, vcc, s56, v124
	v_lshl_add_u64 v[92:93], v[92:93], 0, v[126:127]
	v_cvt_pk_f16_f32 v75, v74, v75
	v_cvt_pk_f16_f32 v74, v72, v73
	v_cvt_pk_f16_f32 v73, v78, v79
	v_cvt_pk_f16_f32 v72, v76, v77
	v_addc_co_u32_e32 v47, vcc, 0, v125, vcc
	global_store_dwordx4 v[92:93], v[72:75], off offset:256 sc1
	v_cvt_pk_f16_f32 v27, v26, v27
	v_cvt_pk_f16_f32 v26, v24, v25
	v_or_b32_e32 v72, 48, v152
	v_cvt_pk_f16_f32 v25, v30, v31
	v_add_co_u32_e32 v30, vcc, s57, v124
	v_ashrrev_i32_e32 v73, 31, v72
	s_nop 0
	v_addc_co_u32_e32 v31, vcc, 0, v125, vcc
	v_lshlrev_b64 v[76:77], 11, v[72:73]
	v_cvt_pk_f16_f32 v11, v10, v11
	v_cvt_pk_f16_f32 v10, v8, v9
	v_cvt_pk_f16_f32 v9, v14, v15
	v_add_co_u32_e32 v14, vcc, 0x58000, v124
	v_lshl_add_u64 v[76:77], s[10:11], 0, v[76:77]
	v_cvt_pk_f16_f32 v56, v60, v61
	v_lshl_add_u64 v[60:61], v[124:125], 0, s[18:19]
	v_cvt_pk_f16_f32 v40, v44, v45
	v_lshl_add_u64 v[44:45], v[124:125], 0, s[20:21]
	v_cvt_pk_f16_f32 v24, v28, v29
	v_lshl_add_u64 v[28:29], v[124:125], 0, s[22:23]
	v_cvt_pk_f16_f32 v8, v12, v13
	v_addc_co_u32_e32 v15, vcc, 0, v125, vcc
	v_cvt_pk_f16_f32 v107, v114, v115
	v_cvt_pk_f16_f32 v106, v112, v113
	v_cvt_pk_f16_f32 v105, v118, v119
	v_cvt_pk_f16_f32 v104, v116, v117
	v_cvt_pk_f16_f32 v91, v98, v99
	v_cvt_pk_f16_f32 v90, v96, v97
	v_cvt_pk_f16_f32 v89, v102, v103
	v_cvt_pk_f16_f32 v88, v100, v101
	v_cvt_pk_f16_f32 v75, v82, v83
	v_cvt_pk_f16_f32 v74, v80, v81
	v_cvt_pk_f16_f32 v73, v86, v87
	v_cvt_pk_f16_f32 v72, v84, v85
	v_lshl_add_u64 v[76:77], v[76:77], 0, v[126:127]
	v_cvt_pk_f16_f32 v67, v66, v67
	v_cvt_pk_f16_f32 v66, v64, v65
	v_cvt_pk_f16_f32 v65, v70, v71
	v_cvt_pk_f16_f32 v64, v68, v69
	global_store_dwordx4 v[60:61], v[40:43], off offset:256 sc1
	global_store_dwordx4 v[44:45], v[24:27], off offset:256 sc1
	global_store_dwordx4 v[28:29], v[8:11], off offset:256 sc1
	v_cvt_pk_f16_f32 v43, v50, v51
	v_cvt_pk_f16_f32 v42, v48, v49
	v_cvt_pk_f16_f32 v41, v54, v55
	v_cvt_pk_f16_f32 v40, v52, v53
	v_cvt_pk_f16_f32 v27, v34, v35
	v_cvt_pk_f16_f32 v26, v32, v33
	v_cvt_pk_f16_f32 v25, v38, v39
	v_cvt_pk_f16_f32 v24, v36, v37
	v_cvt_pk_f16_f32 v11, v18, v19
	v_cvt_pk_f16_f32 v10, v16, v17
	v_cvt_pk_f16_f32 v9, v22, v23
	v_cvt_pk_f16_f32 v8, v20, v21
	v_lshl_add_u64 v[12:13], v[124:125], 0, s[24:25]
	v_cvt_pk_f16_f32 v3, v2, v3
	v_cvt_pk_f16_f32 v2, v0, v1
	v_cvt_pk_f16_f32 v1, v6, v7
	v_cvt_pk_f16_f32 v0, v4, v5
	s_and_b64 vcc, exec, s[6:7]
	s_mov_b32 s61, s59
	s_mov_b32 s58, s60
	s_mov_b64 s[28:29], s[4:5]
	s_mov_b64 s[26:27], s[0:1]
	global_store_dwordx4 v[124:125], v[120:123], off sc1
	global_store_dwordx4 v[108:109], v[104:107], off sc1
	global_store_dwordx4 v[92:93], v[88:91], off sc1
	global_store_dwordx4 v[76:77], v[72:75], off sc1
	global_store_dwordx4 v[76:77], v[64:67], off offset:256 sc1
	global_store_dwordx4 v[62:63], v[56:59], off sc1
	global_store_dwordx4 v[46:47], v[40:43], off sc1
	global_store_dwordx4 v[30:31], v[24:27], off sc1
	global_store_dwordx4 v[14:15], v[8:11], off sc1
	global_store_dwordx4 v[12:13], v[0:3], off offset:256 sc1
	s_cbranch_vccz .LBB0_750
	s_waitcnt vmcnt(0)
	s_cmpk_gt_u32 s33, 0xff
	s_cbranch_scc1 .LBB0_765
	s_barrier

; __device__ __forceinline__ void phase_final(const Params& p) {
;     ...
;     for (int r = gw; r < NTOK; r += 2 * NGW) {
;         const int rr[2] = {r, (r + NGW < NTOK) ? r + NGW : r};
;         f32x4 v[2][4]; h16x4 a[2][4], b[2][4]; float ss[2] = {0.f, 0.f};
; #pragma unroll
;         for (int u = 0; u < 2; ++u)
; #pragma unroll
;             for (int j = 0; j < 4; ++j) { const size_t o = (size_t)rr[u] * DM + 4 * lane + 256 * j; v[u][j] = *(const f32x4*)(p.in[0] + o); a[u][j] = *(const h16x4*)(O1 + o); b[u][j] = *(const h16x4*)(O2 + o); }
.LBB0_823:
	v_add_u32_e32 v22, s10, v12
	v_cmp_gt_i32_e32 vcc, s9, v22
	v_ashrrev_i32_e32 v13, 31, v12
	v_lshlrev_b64 v[24:25], 10, v[12:13]
	v_cndmask_b32_e32 v16, v12, v22, vcc
	v_ashrrev_i32_e32 v17, 31, v16
	v_or_b32_e32 v24, v24, v4
	v_lshlrev_b64 v[42:43], 10, v[16:17]
	v_lshlrev_b64 v[12:13], 12, v[12:13]
	v_lshlrev_b64 v[40:41], 1, v[24:25]
	v_or_b32_e32 v42, v42, v4
	v_lshl_add_u64 v[14:15], v[8:9], 0, v[12:13]
	v_lshl_add_u64 v[12:13], v[24:25], 2, s[16:17]
	v_lshl_add_u64 v[44:45], s[2:3], 0, v[40:41]
	v_lshl_add_u64 v[46:47], s[4:5], 0, v[40:41]
	v_or_b32_e32 v48, 0x200, v40
	v_mov_b32_e32 v49, v41
	v_or_b32_e32 v50, 0x400, v40
	v_mov_b32_e32 v51, v41
	v_or_b32_e32 v40, 0x600, v40
	v_lshlrev_b64 v[60:61], 1, v[42:43]
	global_load_dwordx4 v[0:3], v[6:7], off
	global_load_dwordx4 v[24:27], v[12:13], off
	global_load_dwordx4 v[28:31], v[12:13], off offset:1024
	global_load_dwordx4 v[32:35], v[12:13], off offset:2048
	global_load_dwordx4 v[36:39], v[12:13], off offset:3072
	s_nop 0
	global_load_dwordx2 v[12:13], v[44:45], off
	global_load_dwordx2 v[56:57], v[46:47], off
	v_lshl_add_u64 v[44:45], s[2:3], 0, v[48:49]
	v_lshl_add_u64 v[46:47], s[4:5], 0, v[48:49]
	v_lshl_add_u64 v[48:49], s[2:3], 0, v[50:51]
	v_lshl_add_u64 v[50:51], s[4:5], 0, v[50:51]
	v_lshl_add_u64 v[52:53], s[2:3], 0, v[40:41]
	v_lshl_add_u64 v[40:41], s[4:5], 0, v[40:41]
	v_lshl_add_u64 v[58:59], v[42:43], 2, s[16:17]
	v_lshl_add_u64 v[74:75], s[2:3], 0, v[60:61]
	global_load_dwordx2 v[62:63], v[44:45], off
	global_load_dwordx2 v[64:65], v[46:47], off
	global_load_dwordx2 v[66:67], v[48:49], off
	global_load_dwordx2 v[68:69], v[50:51], off
	global_load_dwordx2 v[70:71], v[52:53], off
	global_load_dwordx2 v[72:73], v[40:41], off
	v_lshl_add_u64 v[76:77], s[4:5], 0, v[60:61]
	global_load_dwordx4 v[40:43], v[58:59], off
	global_load_dwordx4 v[44:47], v[58:59], off offset:1024
	v_or_b32_e32 v78, 0x200, v60
	v_mov_b32_e32 v79, v61
	global_load_dwordx4 v[48:51], v[58:59], off offset:2048
	global_load_dwordx4 v[52:55], v[58:59], off offset:3072
	s_nop 0
	global_load_dwordx2 v[58:59], v[74:75], off
	global_load_dwordx2 v[82:83], v[76:77], off
	v_or_b32_e32 v80, 0x400, v60
	v_mov_b32_e32 v81, v61
	v_or_b32_e32 v60, 0x600, v60
	v_lshl_add_u64 v[74:75], s[2:3], 0, v[78:79]
	v_lshl_add_u64 v[76:77], s[4:5], 0, v[78:79]
	v_lshl_add_u64 v[78:79], s[2:3], 0, v[80:81]
	v_lshl_add_u64 v[80:81], s[4:5], 0, v[80:81]
	v_lshl_add_u64 v[84:85], s[2:3], 0, v[60:61]
	v_lshl_add_u64 v[60:61], s[4:5], 0, v[60:61]
	global_load_dwordx2 v[86:87], v[74:75], off
	global_load_dwordx2 v[88:89], v[76:77], off
	global_load_dwordx2 v[90:91], v[78:79], off
	global_load_dwordx2 v[92:93], v[80:81], off
	global_load_dwordx2 v[94:95], v[84:85], off
	global_load_dwordx2 v[96:97], v[60:61], off
	v_lshlrev_b64 v[16:17], 12, v[16:17]
	v_lshl_add_u64 v[16:17], v[8:9], 0, v[16:17]
	s_waitcnt vmcnt(0)
	v_cvt_f32_f16_e32 v60, v12
	v_cvt_f32_f16_sdwa v61, v12 dst_sel:DWORD dst_unused:UNUSED_PAD src0_sel:WORD_1
	v_cvt_f32_f16_e32 v74, v56
	v_cvt_f32_f16_sdwa v75, v56 dst_sel:DWORD dst_unused:UNUSED_PAD src0_sel:WORD_1
	v_cvt_f32_f16_e32 v12, v13
	v_cvt_f32_f16_sdwa v13, v13 dst_sel:DWORD dst_unused:UNUSED_PAD src0_sel:WORD_1
	v_cvt_f32_f16_e32 v56, v57
	v_cvt_f32_f16_sdwa v57, v57 dst_sel:DWORD dst_unused:UNUSED_PAD src0_sel:WORD_1
	v_cvt_f32_f16_e32 v76, v62
	v_cvt_f32_f16_sdwa v77, v62 dst_sel:DWORD dst_unused:UNUSED_PAD src0_sel:WORD_1
	v_cvt_f32_f16_e32 v78, v64
	v_cvt_f32_f16_sdwa v79, v64 dst_sel:DWORD dst_unused:UNUSED_PAD src0_sel:WORD_1
	v_cvt_f32_f16_e32 v62, v63
	v_cvt_f32_f16_sdwa v63, v63 dst_sel:DWORD dst_unused:UNUSED_PAD src0_sel:WORD_1
	v_cvt_f32_f16_e32 v64, v65
	v_cvt_f32_f16_sdwa v65, v65 dst_sel:DWORD dst_unused:UNUSED_PAD src0_sel:WORD_1
	v_cvt_f32_f16_e32 v80, v66
	v_cvt_f32_f16_sdwa v81, v66 dst_sel:DWORD dst_unused:UNUSED_PAD src0_sel:WORD_1
	v_cvt_f32_f16_e32 v84, v68
	v_cvt_f32_f16_sdwa v85, v68 dst_sel:DWORD dst_unused:UNUSED_PAD src0_sel:WORD_1
	v_cvt_f32_f16_e32 v98, v70
	v_cvt_f32_f16_sdwa v99, v70 dst_sel:DWORD dst_unused:UNUSED_PAD src0_sel:WORD_1
	v_cvt_f32_f16_e32 v100, v72
	v_cvt_f32_f16_sdwa v101, v72 dst_sel:DWORD dst_unused:UNUSED_PAD src0_sel:WORD_1
	v_cvt_f32_f16_e32 v102, v58
	v_cvt_f32_f16_sdwa v103, v58 dst_sel:DWORD dst_unused:UNUSED_PAD src0_sel:WORD_1
	v_cvt_f32_f16_e32 v104, v82
	v_cvt_f32_f16_sdwa v105, v82 dst_sel:DWORD dst_unused:UNUSED_PAD src0_sel:WORD_1
	v_cvt_f32_f16_e32 v58, v59
	v_cvt_f32_f16_sdwa v59, v59 dst_sel:DWORD dst_unused:UNUSED_PAD src0_sel:WORD_1
	v_cvt_f32_f16_e32 v82, v83
	v_cvt_f32_f16_sdwa v83, v83 dst_sel:DWORD dst_unused:UNUSED_PAD src0_sel:WORD_1
	v_cvt_f32_f16_e32 v106, v86
	v_cvt_f32_f16_sdwa v107, v86 dst_sel:DWORD dst_unused:UNUSED_PAD src0_sel:WORD_1
	v_cvt_f32_f16_e32 v108, v88
	v_cvt_f32_f16_sdwa v109, v88 dst_sel:DWORD dst_unused:UNUSED_PAD src0_sel:WORD_1
	v_cvt_f32_f16_e32 v66, v67
	v_cvt_f32_f16_sdwa v67, v67 dst_sel:DWORD dst_unused:UNUSED_PAD src0_sel:WORD_1
	v_cvt_f32_f16_e32 v68, v69
	v_cvt_f32_f16_sdwa v69, v69 dst_sel:DWORD dst_unused:UNUSED_PAD src0_sel:WORD_1
	v_cvt_f32_f16_e32 v86, v87
	v_cvt_f32_f16_sdwa v87, v87 dst_sel:DWORD dst_unused:UNUSED_PAD src0_sel:WORD_1
	v_cvt_f32_f16_e32 v88, v89
	v_cvt_f32_f16_sdwa v89, v89 dst_sel:DWORD dst_unused:UNUSED_PAD src0_sel:WORD_1
	v_cvt_f32_f16_e32 v110, v90
	v_cvt_f32_f16_sdwa v111, v90 dst_sel:DWORD dst_unused:UNUSED_PAD src0_sel:WORD_1
	v_cvt_f32_f16_e32 v112, v92
	v_cvt_f32_f16_sdwa v113, v92 dst_sel:DWORD dst_unused:UNUSED_PAD src0_sel:WORD_1
	v_cvt_f32_f16_e32 v114, v94
	v_cvt_f32_f16_sdwa v115, v94 dst_sel:DWORD dst_unused:UNUSED_PAD src0_sel:WORD_1
	v_cvt_f32_f16_e32 v116, v96
; __device__ __forceinline__ void phase_final(const Params& p) {
;     ...
; #pragma unroll
;         for (int u = 0; u < 2; ++u)
; #pragma unroll
;             for (int j = 0; j < 4; ++j) {
; #pragma unroll
;                 for (int e = 0; e < 4; ++e) v[u][j][e] += (float)a[u][j][e] + (float)b[u][j][e];
;                 ss[u] += v[u][j][0] * v[u][j][0] + v[u][j][1] * v[u][j][1] + v[u][j][2] * v[u][j][2] + v[u][j][3] * v[u][j][3]; }
	v_cvt_f32_f16_sdwa v117, v96 dst_sel:DWORD dst_unused:UNUSED_PAD src0_sel:WORD_1
	v_pk_add_f32 v[60:61], v[60:61], v[74:75]
	v_pk_add_f32 v[12:13], v[12:13], v[56:57]
	v_cvt_f32_f16_e32 v70, v71
	v_cvt_f32_f16_sdwa v71, v71 dst_sel:DWORD dst_unused:UNUSED_PAD src0_sel:WORD_1
	v_cvt_f32_f16_e32 v72, v73
	v_cvt_f32_f16_sdwa v73, v73 dst_sel:DWORD dst_unused:UNUSED_PAD src0_sel:WORD_1
	v_cvt_f32_f16_e32 v90, v91
	v_cvt_f32_f16_sdwa v91, v91 dst_sel:DWORD dst_unused:UNUSED_PAD src0_sel:WORD_1
	v_cvt_f32_f16_e32 v92, v93
	v_cvt_f32_f16_sdwa v93, v93 dst_sel:DWORD dst_unused:UNUSED_PAD src0_sel:WORD_1
	v_cvt_f32_f16_e32 v94, v95
	v_cvt_f32_f16_sdwa v95, v95 dst_sel:DWORD dst_unused:UNUSED_PAD src0_sel:WORD_1
	v_cvt_f32_f16_e32 v96, v97
	v_cvt_f32_f16_sdwa v97, v97 dst_sel:DWORD dst_unused:UNUSED_PAD src0_sel:WORD_1
	v_pk_add_f32 v[24:25], v[24:25], v[60:61]
	v_pk_add_f32 v[12:13], v[26:27], v[12:13]
	v_pk_add_f32 v[26:27], v[76:77], v[78:79]
	v_pk_add_f32 v[56:57], v[62:63], v[64:65]
	v_pk_add_f32 v[60:61], v[80:81], v[84:85]
	v_pk_add_f32 v[64:65], v[98:99], v[100:101]
	v_pk_add_f32 v[58:59], v[58:59], v[82:83]
	v_pk_add_f32 v[28:29], v[28:29], v[26:27]
	v_pk_add_f32 v[32:33], v[32:33], v[60:61]
	v_pk_add_f32 v[36:37], v[36:37], v[64:65]
	v_pk_add_f32 v[60:61], v[102:103], v[104:105]
	v_pk_add_f32 v[42:43], v[42:43], v[58:59]
	v_pk_add_f32 v[58:59], v[106:107], v[108:109]
	v_pk_add_f32 v[62:63], v[66:67], v[68:69]
	v_pk_add_f32 v[30:31], v[30:31], v[56:57]
	v_mov_b32_e32 v56, v25
	v_mov_b32_e32 v57, v29
	v_mov_b32_e32 v64, v33
	v_mov_b32_e32 v65, v37
	v_pk_add_f32 v[40:41], v[40:41], v[60:61]
	v_pk_add_f32 v[60:61], v[86:87], v[88:89]
	v_pk_add_f32 v[74:75], v[110:111], v[112:113]
	v_pk_add_f32 v[78:79], v[114:115], v[116:117]
	v_pk_add_f32 v[44:45], v[44:45], v[58:59]
	v_mov_b32_e32 v26, v24
	v_pk_add_f32 v[34:35], v[34:35], v[62:63]
	v_mov_b32_e32 v27, v28
	v_mov_b32_e32 v62, v32
	v_mov_b32_e32 v63, v36
	v_pk_mul_f32 v[56:57], v[56:57], v[56:57]
	v_pk_mul_f32 v[64:65], v[64:65], v[64:65]
	v_pk_add_f32 v[46:47], v[46:47], v[60:61]
	v_mov_b32_e32 v60, v41
	v_pk_add_f32 v[48:49], v[48:49], v[74:75]
	v_pk_add_f32 v[52:53], v[52:53], v[78:79]
	v_mov_b32_e32 v61, v45
	v_pk_add_f32 v[66:67], v[70:71], v[72:73]
	v_pk_add_f32 v[76:77], v[90:91], v[92:93]
	v_pk_add_f32 v[80:81], v[94:95], v[96:97]
	v_mov_b32_e32 v58, v40
	v_pk_fma_f32 v[26:27], v[26:27], v[26:27], v[56:57]
	v_pk_fma_f32 v[56:57], v[62:63], v[62:63], v[64:65]
	v_mov_b32_e32 v59, v44
	v_mov_b32_e32 v64, v49
	v_mov_b32_e32 v65, v53
	v_pk_mul_f32 v[60:61], v[60:61], v[60:61]
	v_mov_b32_e32 v68, v12
	v_pk_add_f32 v[38:39], v[38:39], v[66:67]
	v_mov_b32_e32 v69, v30
	v_mov_b32_e32 v82, v42
	v_pk_add_f32 v[50:51], v[50:51], v[76:77]
	v_pk_add_f32 v[54:55], v[54:55], v[80:81]
	v_mov_b32_e32 v83, v46
	v_mov_b32_e32 v62, v48
	v_mov_b32_e32 v63, v52
	v_pk_mul_f32 v[64:65], v[64:65], v[64:65]
	v_pk_fma_f32 v[58:59], v[58:59], v[58:59], v[60:61]
	v_mov_b32_e32 v70, v13
	v_mov_b32_e32 v71, v31
	v_mov_b32_e32 v66, v34
	v_mov_b32_e32 v67, v38
	v_mov_b32_e32 v84, v43
	v_mov_b32_e32 v85, v47
	v_mov_b32_e32 v74, v50
	v_mov_b32_e32 v75, v54
	v_pk_fma_f32 v[26:27], v[68:69], v[68:69], v[26:27]
	v_pk_fma_f32 v[60:61], v[62:63], v[62:63], v[64:65]
	v_pk_fma_f32 v[58:59], v[82:83], v[82:83], v[58:59]
	v_mov_b32_e32 v72, v35
	v_mov_b32_e32 v73, v39
	v_mov_b32_e32 v76, v51
	v_mov_b32_e32 v77, v55
	v_pk_fma_f32 v[56:57], v[66:67], v[66:67], v[56:57]
	v_pk_fma_f32 v[26:27], v[70:71], v[70:71], v[26:27]
	v_pk_fma_f32 v[60:61], v[74:75], v[74:75], v[60:61]
	v_pk_fma_f32 v[58:59], v[84:85], v[84:85], v[58:59]
	v_pk_fma_f32 v[56:57], v[72:73], v[72:73], v[56:57]
	v_mov_b32_e32 v63, v26
	v_pk_fma_f32 v[60:61], v[76:77], v[76:77], v[60:61]
	v_mov_b32_e32 v62, v58
	v_mov_b32_e32 v26, v59
	v_mov_b32_e32 v65, v56
	v_mov_b32_e32 v64, v60
	v_pk_add_f32 v[26:27], v[62:63], v[26:27]
	v_mov_b32_e32 v56, v61
	v_pk_add_f32 v[26:27], v[26:27], v[64:65]
	s_nop 0
	v_pk_add_f32 v[26:27], v[26:27], v[56:57]
	ds_bpermute_b32 v57, v5, v27
	ds_bpermute_b32 v56, v5, v26
	s_waitcnt lgkmcnt(0)
; __device__ __forceinline__ void phase_final(const Params& p) {
;     ...
; #pragma unroll
;         for (int o = 1; o < 64; o <<= 1) { ss[0] += __shfl_xor(ss[0], o); ss[1] += __shfl_xor(ss[1], o); }
;         const float rs[2] = {rsqrtf(ss[0] * (1.f / 1024.f) + 1e-6f), rsqrtf(ss[1] * (1.f / 1024.f) + 1e-6f)};
; #pragma unroll
;         for (int j = 0; j < 4; ++j) { const f32x4 gg = *(const f32x4*)(g + 4 * lane + 256 * j);
; #pragma unroll
;             for (int u = 0; u < 2; ++u) { f32x4 o = v[u][j] * rs[u]; o = o * gg; *(f32x4*)(p.out + (size_t)rr[u] * DM + 4 * lane + 256 * j) = o; } }
	v_pk_add_f32 v[26:27], v[26:27], v[56:57]
	ds_bpermute_b32 v57, v11, v27
	ds_bpermute_b32 v56, v11, v26
	s_waitcnt lgkmcnt(0)
	v_pk_add_f32 v[26:27], v[26:27], v[56:57]
	ds_bpermute_b32 v57, v18, v27
	ds_bpermute_b32 v56, v18, v26
	s_waitcnt lgkmcnt(0)
	v_pk_add_f32 v[26:27], v[26:27], v[56:57]
	ds_bpermute_b32 v57, v19, v27
	ds_bpermute_b32 v56, v19, v26
	s_waitcnt lgkmcnt(0)
	v_pk_add_f32 v[26:27], v[26:27], v[56:57]
	ds_bpermute_b32 v57, v20, v27
	ds_bpermute_b32 v56, v20, v26
	s_waitcnt lgkmcnt(0)
	v_pk_add_f32 v[26:27], v[26:27], v[56:57]
	ds_bpermute_b32 v57, v21, v27
	ds_bpermute_b32 v56, v21, v26
	s_waitcnt lgkmcnt(0)
	v_pk_add_f32 v[26:27], v[26:27], v[56:57]
	s_nop 0
	v_pk_fma_f32 v[26:27], v[26:27], s[8:9], v[10:11] op_sel_hi:[1,0,0]
	s_nop 0
	v_mul_f32_e32 v23, 0x4b800000, v27
	v_cmp_gt_f32_e64 s[0:1], s11, v27
	v_mul_f32_e32 v56, 0x4b800000, v26
	v_cmp_gt_f32_e32 vcc, s11, v26
	v_cndmask_b32_e64 v23, v27, v23, s[0:1]
	v_rsq_f32_e32 v23, v23
	v_cndmask_b32_e32 v26, v26, v56, vcc
	v_rsq_f32_e32 v26, v26
	v_mul_f32_e32 v27, 0x45800000, v23
	v_cndmask_b32_e64 v56, v23, v27, s[0:1]
	v_mul_f32_e32 v57, 0x45800000, v26
	v_cndmask_b32_e32 v58, v26, v57, vcc
	v_pk_mul_f32 v[24:25], v[24:25], v[56:57] op_sel_hi:[1,0]
	v_pk_mul_f32 v[12:13], v[12:13], v[56:57] op_sel_hi:[1,0]
	v_pk_mul_f32 v[40:41], v[40:41], v[58:59] op_sel_hi:[1,0]
	v_pk_mul_f32 v[42:43], v[42:43], v[58:59] op_sel_hi:[1,0]
	v_pk_mul_f32 v[26:27], v[2:3], v[12:13]
	v_pk_mul_f32 v[24:25], v[0:1], v[24:25]
	v_pk_mul_f32 v[2:3], v[2:3], v[42:43]
	v_pk_mul_f32 v[0:1], v[0:1], v[40:41]
	global_store_dwordx4 v[14:15], v[24:27], off sc1
	global_store_dwordx4 v[16:17], v[0:3], off sc1
	global_load_dwordx4 v[0:3], v[6:7], off offset:1024
	v_pk_mul_f32 v[12:13], v[30:31], v[56:57] op_sel_hi:[1,0]
	v_pk_mul_f32 v[24:25], v[28:29], v[56:57] op_sel_hi:[1,0]
	v_pk_mul_f32 v[28:29], v[46:47], v[58:59] op_sel_hi:[1,0]
	v_pk_mul_f32 v[30:31], v[44:45], v[58:59] op_sel_hi:[1,0]
	s_waitcnt vmcnt(0)
	v_pk_mul_f32 v[24:25], v[0:1], v[24:25]
	v_pk_mul_f32 v[26:27], v[2:3], v[12:13]
	v_pk_mul_f32 v[0:1], v[0:1], v[30:31]
	v_pk_mul_f32 v[2:3], v[2:3], v[28:29]
	global_store_dwordx4 v[14:15], v[24:27], off offset:1024 sc1
	global_store_dwordx4 v[16:17], v[0:3], off offset:1024 sc1
	global_load_dwordx4 v[0:3], v[6:7], off offset:2048
	v_pk_mul_f32 v[12:13], v[34:35], v[56:57] op_sel_hi:[1,0]
	v_pk_mul_f32 v[24:25], v[32:33], v[56:57] op_sel_hi:[1,0]
	v_pk_mul_f32 v[28:29], v[50:51], v[58:59] op_sel_hi:[1,0]
	v_pk_mul_f32 v[30:31], v[48:49], v[58:59] op_sel_hi:[1,0]
	s_waitcnt vmcnt(0)
	v_pk_mul_f32 v[24:25], v[0:1], v[24:25]
	v_pk_mul_f32 v[26:27], v[2:3], v[12:13]
	v_pk_mul_f32 v[0:1], v[0:1], v[30:31]
	v_pk_mul_f32 v[2:3], v[2:3], v[28:29]
	global_store_dwordx4 v[14:15], v[24:27], off offset:2048 sc1
	global_store_dwordx4 v[16:17], v[0:3], off offset:2048 sc1
	global_load_dwordx4 v[0:3], v[6:7], off offset:3072
	v_add_u32_e32 v12, s10, v22
	v_cmp_lt_i32_e32 vcc, s12, v12
	v_pk_mul_f32 v[24:25], v[38:39], v[56:57] op_sel_hi:[1,0]
	v_pk_mul_f32 v[22:23], v[36:37], v[56:57] op_sel_hi:[1,0]
	s_or_b64 s[6:7], vcc, s[6:7]
	v_pk_mul_f32 v[26:27], v[54:55], v[58:59] op_sel_hi:[1,0]
	v_pk_mul_f32 v[28:29], v[52:53], v[58:59] op_sel_hi:[1,0]
	s_waitcnt vmcnt(0)
	v_pk_mul_f32 v[22:23], v[0:1], v[22:23]
	v_pk_mul_f32 v[24:25], v[2:3], v[24:25]
	v_pk_mul_f32 v[0:1], v[0:1], v[28:29]
	v_pk_mul_f32 v[2:3], v[2:3], v[26:27]
	global_store_dwordx4 v[14:15], v[22:25], off offset:3072 sc1
	global_store_dwordx4 v[16:17], v[0:3], off offset:3072 sc1
	s_andn2_b64 exec, exec, s[6:7]
	s_cbranch_execnz .LBB0_823
